# attention: K blocks loaded as whole rows and transposed through the per-wave LDS stage (gather-pattern fragment loads cost 3x), late K/V loads issued earlier into freed window slots and unused P regis
# speedup vs baseline: 1.0132x; 1.0132x over previous
.Latt_entry:
	s_mov_b64 exec, -1
	v_readlane_b32 s4, v254, 0
	v_readlane_b32 s5, v254, 1
	v_readlane_b32 s6, v254, 42
	v_readlane_b32 s7, v254, 43
	v_readlane_b32 s8, v254, 46
	v_readlane_b32 s10, v254, 53
	v_readfirstlane_b32 s0, v145
	s_movk_i32 s78, 0x90
	s_movk_i32 s79, 0x110
	s_mov_b32 s80, 0x12100
	s_movk_i32 s82, 0x4000
	s_movk_i32 s83, 0x1000
	s_mov_b32 s84, 0xc000
	s_mov_b32 s85, 0x7ffff000
	s_mov_b32 s70, 0x42a00000
	s_mov_b32 s71, 0xf149f2ca
	s_mov_b32 s72, 0x3fb8aa3b
	s_mov_b32 s73, 0x3fb8aa3b
	s_lshr_b32 s0, s0, 6
	s_mul_i32 s1, s0, 0x1200
	s_add_i32 s1, s1, 0x12500
	s_mov_b32 s37, 0
	v_and_b32_e32 v142, 63, v145
	v_and_b32_e32 v160, 15, v145
	v_bfe_u32 v134, v145, 4, 2
	v_lshlrev_b32_e32 v161, 4, v134
	v_lshlrev_b32_e32 v169, 2, v134
	v_and_b32_e32 v135, 7, v145
	v_lshlrev_b32_e32 v162, 4, v135
	v_bfe_u32 v164, v145, 3, 3
	v_and_b32_e32 v136, 3, v164
	v_lshl_add_u32 v178, v136, 7, v162
	v_mad_u32_u24 v175, v160, s78, v161
	v_add_u32_e32 v175, s1, v175
	v_mad_u32_u24 v165, v164, s78, v162
	v_add_u32_e32 v165, s1, v165
	v_bfe_u32 v134, v145, 2, 2
	v_add_u32_e32 v134, v134, v169
	v_and_b32_e32 v135, 3, v145
	v_lshlrev_b32_e32 v135, 3, v135
	v_mad_u32_u24 v166, v134, s78, v135
	v_add_u32_e32 v166, s1, v166
	v_xor_b32_e32 v134, 16, v142
	v_lshlrev_b32_e32 v167, 2, v134
	v_xor_b32_e32 v134, 32, v142
	v_lshlrev_b32_e32 v168, 2, v134
	v_sub_u32_e32 v134, v169, v160
	v_cmp_ge_i32_e64 s[54:55], v134, 0
	v_cmp_le_i32_e64 s[62:63], v134, 0
	v_cmp_ge_i32_e64 s[56:57], v134, -1
	v_cmp_le_i32_e64 s[64:65], v134, -1
	v_cmp_ge_i32_e64 s[58:59], v134, -2
	v_cmp_le_i32_e64 s[66:67], v134, -2
	v_cmp_ge_i32_e64 s[60:61], v134, -3
	v_cmp_le_i32_e64 s[68:69], v134, -3
	v_lshrrev_b32_e32 v134, 1, v145
	v_lshrrev_b32_e32 v135, 4, v134
	v_add_u32_e32 v135, v135, v134
	v_and_b32_e32 v136, 1, v145
	v_lshlrev_b32_e32 v137, 7, v136
	v_mad_u32_u24 v170, v135, s79, v137
	v_lshl_add_u32 v171, v134, 2, s80
	v_lshlrev_b32_e32 v135, 11, v134
	v_lshl_add_u32 v172, v136, 6, v135
	s_lshl_b32 s2, s0, 5
	v_add_u32_e32 v134, s2, v160
	v_mad_u32_u24 v149, v134, s78, v161
	v_bfe_u32 v134, v145, 2, 2
	v_add_u32_e32 v134, v134, v169
	v_add_u32_e32 v134, s2, v134
	v_and_b32_e32 v135, 3, v145
	v_lshlrev_b32_e32 v135, 3, v135
	v_mad_u32_u24 v151, v134, s78, v135
	v_add_u32_e32 v151, 0xd800, v151
	s_mul_i32 s2, s0, 48
	v_add_u32_e32 v134, s2, v164
	v_mad_u32_u24 v253, v134, s78, v162
	v_mov_b32_e32 v130, 0
	v_mov_b32_e32 v131, 0
	v_mov_b32_e32 v184, 0
	v_mov_b32_e32 v185, 0
	s_lshr_b32 s2, s10, 3
	s_and_b32 s3, s10, 7
	s_and_b32 s30, s2, 31
	s_lshl_b32 s31, s3, 5
	s_or_b32 s31, s31, s30
	s_lshr_b32 s30, s10, 8
	s_cmp_eq_u32 s8, 0x100
	s_cselect_b32 s2, s31, s2
	s_cselect_b32 s17, s30, s3
	s_lshl_b32 s16, s2, 8
	s_cmp_lt_u32 s2, 0x80
	s_cselect_b32 s12, s82, s83
	s_cselect_b32 s13, 12, 10
	s_cselect_b32 s3, s84, s85
	s_and_b32 s3, s16, s3
	s_sub_i32 s15, s16, s3
	s_lshr_b32 s30, s12, 4
	s_add_i32 s14, s30, -1
	s_lshl_b32 s30, s17, 23
	s_lshl_b32 s3, s3, 7
	s_add_u32 s30, s30, s3
	s_add_u32 s18, s4, s30
	s_addc_u32 s19, s5, 0
	s_add_u32 s20, s18, 0x4000000
	s_addc_u32 s21, s19, 0
	s_add_u32 s22, s18, 0x8000000
	s_addc_u32 s23, s19, 0
	s_lshl_b32 s2, s0, 5
	s_add_i32 s42, s15, s2
	s_mov_b32 s43, 0
	v_add_u32_e32 v134, s42, v160
	v_add_u32_e32 v134, s43, v134
	v_subrev_u32_e32 v135, s15, v134
	v_lshrrev_b32_e32 v136, 4, v135
	v_add_u32_e32 v136, v136, v135
	v_mad_u32_u24 v176, v136, s79, v161
	v_lshl_add_u32 v177, v135, 2, s80
	s_mul_i32 s2, s0, 48
	s_add_i32 s2, s2, s15
	s_add_i32 s2, s2, -64
	v_add_u32_e32 v138, s2, v164
	v_and_b32_e32 v139, 3, v138
	v_lshlrev_b32_e32 v139, s13, v139
	v_bfe_u32 v140, v138, 2, 2
	v_add_u32_e32 v139, v139, v140
	v_lshl_add_u32 v139, v139, 7, v162
	v_ashrrev_i32_e32 v138, 4, v138
	v_med3_i32 v138, v138, 0, s14
	v_lshl_add_u32 v138, v138, 9, v139
	global_load_dwordx4 v[0:3], v138, s[20:21]
	s_mul_i32 s2, s0, 48
	s_add_i32 s2, s2, s15
	s_add_i32 s2, s2, -56
	v_add_u32_e32 v138, s2, v164
	v_and_b32_e32 v139, 3, v138
	v_lshlrev_b32_e32 v139, s13, v139
	v_bfe_u32 v140, v138, 2, 2
	v_add_u32_e32 v139, v139, v140
	v_lshl_add_u32 v139, v139, 7, v162
	v_ashrrev_i32_e32 v138, 4, v138
	v_med3_i32 v138, v138, 0, s14
	v_lshl_add_u32 v138, v138, 9, v139
	global_load_dwordx4 v[4:7], v138, s[20:21]
	s_mul_i32 s2, s0, 48
	s_add_i32 s2, s2, s15
	s_add_i32 s2, s2, -48
	v_add_u32_e32 v138, s2, v164
	v_and_b32_e32 v139, 3, v138
	v_lshlrev_b32_e32 v139, s13, v139
	v_bfe_u32 v140, v138, 2, 2
	v_add_u32_e32 v139, v139, v140
	v_lshl_add_u32 v139, v139, 7, v162
	v_ashrrev_i32_e32 v138, 4, v138
	v_med3_i32 v138, v138, 0, s14
	v_lshl_add_u32 v138, v138, 9, v139
	global_load_dwordx4 v[8:11], v138, s[20:21]
	s_mul_i32 s2, s0, 48
	s_add_i32 s2, s2, s15
	s_add_i32 s2, s2, -40
	v_add_u32_e32 v138, s2, v164
	v_and_b32_e32 v139, 3, v138
	v_lshlrev_b32_e32 v139, s13, v139
	v_bfe_u32 v140, v138, 2, 2
	v_add_u32_e32 v139, v139, v140
	v_lshl_add_u32 v139, v139, 7, v162
	v_ashrrev_i32_e32 v138, 4, v138
	v_med3_i32 v138, v138, 0, s14
	v_lshl_add_u32 v138, v138, 9, v139
	global_load_dwordx4 v[12:15], v138, s[20:21]
	s_lshl_b32 s2, s0, 5
	s_add_i32 s2, s2, s15
	s_add_i32 s2, s2, 0
	v_add_u32_e32 v138, s2, v164
	v_and_b32_e32 v139, 3, v138
	v_lshlrev_b32_e32 v139, s13, v139
	v_lshrrev_b32_e32 v140, 2, v138
	v_add_u32_e32 v139, v139, v140
	v_lshl_add_u32 v139, v139, 7, v162
	global_load_dwordx4 v[48:51], v139, s[18:19]
	s_lshl_b32 s2, s0, 5
	s_add_i32 s2, s2, s15
	s_add_i32 s2, s2, 8
	v_add_u32_e32 v138, s2, v164
	v_and_b32_e32 v139, 3, v138
	v_lshlrev_b32_e32 v139, s13, v139
	v_lshrrev_b32_e32 v140, 2, v138
	v_add_u32_e32 v139, v139, v140
	v_lshl_add_u32 v139, v139, 7, v162
	global_load_dwordx4 v[52:55], v139, s[18:19]
	s_lshl_b32 s2, s0, 5
	s_add_i32 s2, s2, s15
	s_add_i32 s2, s2, 16
	v_add_u32_e32 v138, s2, v164
	v_and_b32_e32 v139, 3, v138
	v_lshlrev_b32_e32 v139, s13, v139
	v_lshrrev_b32_e32 v140, 2, v138
	v_add_u32_e32 v139, v139, v140
	v_lshl_add_u32 v139, v139, 7, v162
	global_load_dwordx4 v[56:59], v139, s[18:19]
	s_lshl_b32 s2, s0, 5
	s_add_i32 s2, s2, s15
	s_add_i32 s2, s2, 24
	v_add_u32_e32 v138, s2, v164
	v_and_b32_e32 v139, 3, v138
	v_lshlrev_b32_e32 v139, s13, v139
	v_lshrrev_b32_e32 v140, 2, v138
	v_add_u32_e32 v139, v139, v140
	v_lshl_add_u32 v139, v139, 7, v162
	global_load_dwordx4 v[60:63], v139, s[18:19]
	s_mul_i32 s2, s0, 48
	s_add_i32 s2, s2, s15
	s_add_i32 s2, s2, -32
	v_add_u32_e32 v138, s2, v164
	v_and_b32_e32 v139, 3, v138
	v_lshlrev_b32_e32 v139, s13, v139
	v_bfe_u32 v140, v138, 2, 2
	v_add_u32_e32 v139, v139, v140
	v_lshl_add_u32 v139, v139, 7, v162
	v_ashrrev_i32_e32 v138, 4, v138
	v_med3_i32 v138, v138, 0, s14
	v_lshl_add_u32 v138, v138, 9, v139
	global_load_dwordx4 v[16:19], v138, s[20:21]
	s_mul_i32 s2, s0, 48
	s_add_i32 s2, s2, s15
	s_add_i32 s2, s2, -24
	v_add_u32_e32 v138, s2, v164
	v_and_b32_e32 v139, 3, v138
	v_lshlrev_b32_e32 v139, s13, v139
	v_bfe_u32 v140, v138, 2, 2
	v_add_u32_e32 v139, v139, v140
	v_lshl_add_u32 v139, v139, 7, v162
	v_ashrrev_i32_e32 v138, 4, v138
	v_med3_i32 v138, v138, 0, s14
	v_lshl_add_u32 v138, v138, 9, v139
	global_load_dwordx4 v[20:23], v138, s[20:21]
	s_mul_i32 s2, s0, 48
	s_add_i32 s2, s2, s15
	s_add_i32 s2, s2, -64
	v_add_u32_e32 v138, s2, v164
	v_and_b32_e32 v139, 3, v138
	v_lshlrev_b32_e32 v139, s13, v139
	v_bfe_u32 v140, v138, 2, 2
	v_add_u32_e32 v139, v139, v140
	v_lshl_add_u32 v139, v139, 7, v162
	v_ashrrev_i32_e32 v138, 4, v138
	v_med3_i32 v138, v138, 0, s14
	v_lshl_add_u32 v138, v138, 9, v139
	global_load_dwordx4 v[24:27], v138, s[22:23]
	s_mul_i32 s2, s0, 48
	s_add_i32 s2, s2, s15
	s_add_i32 s2, s2, -56
	v_add_u32_e32 v138, s2, v164
	v_and_b32_e32 v139, 3, v138
	v_lshlrev_b32_e32 v139, s13, v139
	v_bfe_u32 v140, v138, 2, 2
	v_add_u32_e32 v139, v139, v140
	v_lshl_add_u32 v139, v139, 7, v162
	v_ashrrev_i32_e32 v138, 4, v138
	v_med3_i32 v138, v138, 0, s14
	v_lshl_add_u32 v138, v138, 9, v139
	global_load_dwordx4 v[28:31], v138, s[22:23]
	s_mul_i32 s2, s0, 48
	s_add_i32 s2, s2, s15
	s_add_i32 s2, s2, -48
	v_add_u32_e32 v138, s2, v164
	v_and_b32_e32 v139, 3, v138
	v_lshlrev_b32_e32 v139, s13, v139
	v_bfe_u32 v140, v138, 2, 2
	v_add_u32_e32 v139, v139, v140
	v_lshl_add_u32 v139, v139, 7, v162
	v_ashrrev_i32_e32 v138, 4, v138
	v_med3_i32 v138, v138, 0, s14
	v_lshl_add_u32 v138, v138, 9, v139
	global_load_dwordx4 v[32:35], v138, s[22:23]
	s_mul_i32 s2, s0, 48
	s_add_i32 s2, s2, s15
	s_add_i32 s2, s2, -40
	v_add_u32_e32 v138, s2, v164
	v_and_b32_e32 v139, 3, v138
	v_lshlrev_b32_e32 v139, s13, v139
	v_bfe_u32 v140, v138, 2, 2
	v_add_u32_e32 v139, v139, v140
	v_lshl_add_u32 v139, v139, 7, v162
	v_ashrrev_i32_e32 v138, 4, v138
	v_med3_i32 v138, v138, 0, s14
	v_lshl_add_u32 v138, v138, 9, v139
	global_load_dwordx4 v[36:39], v138, s[22:23]
	s_mul_i32 s2, s0, 48
	s_add_i32 s2, s2, s15
	s_add_i32 s2, s2, -32
	v_add_u32_e32 v138, s2, v164
	v_and_b32_e32 v139, 3, v138
	v_lshlrev_b32_e32 v139, s13, v139
	v_bfe_u32 v140, v138, 2, 2
	v_add_u32_e32 v139, v139, v140
	v_lshl_add_u32 v139, v139, 7, v162
	v_ashrrev_i32_e32 v138, 4, v138
	v_med3_i32 v138, v138, 0, s14
	v_lshl_add_u32 v138, v138, 9, v139
	global_load_dwordx4 v[40:43], v138, s[22:23]
	s_mul_i32 s2, s0, 48
	s_add_i32 s2, s2, s15
	s_add_i32 s2, s2, -24
	v_add_u32_e32 v138, s2, v164
	v_and_b32_e32 v139, 3, v138
	v_lshlrev_b32_e32 v139, s13, v139
	v_bfe_u32 v140, v138, 2, 2
	v_add_u32_e32 v139, v139, v140
	v_lshl_add_u32 v139, v139, 7, v162
	v_ashrrev_i32_e32 v138, 4, v138
	v_med3_i32 v138, v138, 0, s14
	v_lshl_add_u32 v138, v138, 9, v139
	global_load_dwordx4 v[44:47], v138, s[22:23]
	s_waitcnt vmcnt(0)
.Latt_unit:
	s_mov_b32 s33, s12
	s_mov_b32 s34, s15
	s_mov_b32 s35, s16
	s_mov_b32 s36, s17
	s_mov_b32 s38, s14
	s_mov_b32 s39, s13
	s_mov_b32 s24, s20
	s_mov_b32 s25, s21
	s_mov_b32 s26, s22
	s_mov_b32 s27, s23
	s_mov_b32 s40, s42
	s_mov_b32 s41, s43
	v_mov_b32_e32 v173, v176
	v_mov_b32_e32 v174, v177
	s_lshr_b32 s44, s33, 0
	s_lshr_b32 s2, s0, 2
	s_lshl_b32 s2, s2, 5
	s_lshr_b32 s3, s15, 2
	s_add_i32 s42, s3, s2
	s_and_b32 s43, s0, 3
	s_waitcnt vmcnt(4)
	ds_write_b128 v253, v[0:3]
	ds_write_b128 v253, v[4:7] offset:1152
	ds_write_b128 v253, v[8:11] offset:2304
	ds_write_b128 v253, v[12:15] offset:3456
	ds_write_b128 v253, v[16:19] offset:4608
	ds_write_b128 v253, v[20:23] offset:5760
	ds_write_b128 v253, v[24:27] offset:55296
	ds_write_b128 v253, v[28:31] offset:56448
	ds_write_b128 v253, v[32:35] offset:57600
	ds_write_b128 v253, v[36:39] offset:58752
	ds_write_b128 v253, v[40:43] offset:59904
	ds_write_b128 v253, v[44:47] offset:61056
	s_lshl_b32 s2, s0, 12
	s_add_i32 s2, s2, 0x1b500
	v_and_b32_e32 v141, 63, v145
	v_lshl_add_u32 v141, v141, 4, s2
	ds_write_b128 v141, v[48:51]
	ds_write_b128 v141, v[52:55] offset:1024
	ds_write_b128 v141, v[56:59] offset:2048
	ds_write_b128 v141, v[60:63] offset:3072
	s_waitcnt lgkmcnt(0)
	s_barrier
	v_add_u32_e32 v134, s42, v160
	v_lshlrev_b32_e32 v134, 2, v134
	v_add_u32_e32 v134, s43, v134
	v_subrev_u32_e32 v135, s15, v134
	v_lshrrev_b32_e32 v136, 4, v135
	v_add_u32_e32 v136, v136, v135
	v_mad_u32_u24 v176, v136, s79, v161
	v_lshl_add_u32 v177, v135, 2, s80
	s_lshl_b32 s2, s43, s13
	s_lshl_b32 s2, s2, 7
	s_add_u32 s86, s20, s2
	s_addc_u32 s87, s21, 0
	s_add_i32 s2, s42, -64
	v_add_u32_e32 v136, s2, v164
	v_ashrrev_i32_e32 v136, 2, v136
	v_med3_i32 v136, v136, 0, s14
	v_lshl_add_u32 v136, v136, 9, v178
	global_load_dwordx4 v[0:3], v136, s[86:87]
	s_add_i32 s2, s42, -56
	v_add_u32_e32 v135, s2, v164
	v_ashrrev_i32_e32 v135, 2, v135
	v_med3_i32 v135, v135, 0, s14
	v_lshl_add_u32 v135, v135, 9, v178
	global_load_dwordx4 v[4:7], v135, s[86:87]
	s_add_i32 s2, s42, -48
	v_add_u32_e32 v136, s2, v164
	v_ashrrev_i32_e32 v136, 2, v136
	v_med3_i32 v136, v136, 0, s14
	v_lshl_add_u32 v136, v136, 9, v178
	global_load_dwordx4 v[8:11], v136, s[86:87]
	s_add_i32 s2, s42, -40
	v_add_u32_e32 v135, s2, v164
	v_ashrrev_i32_e32 v135, 2, v135
	v_med3_i32 v135, v135, 0, s14
	v_lshl_add_u32 v135, v135, 9, v178
	global_load_dwordx4 v[12:15], v135, s[86:87]
	s_add_i32 s2, s42, -32
	v_add_u32_e32 v136, s2, v164
	v_ashrrev_i32_e32 v136, 2, v136
	v_med3_i32 v136, v136, 0, s14
	v_lshl_add_u32 v136, v136, 9, v178
	global_load_dwordx4 v[16:19], v136, s[86:87]
	s_add_i32 s2, s42, -24
	v_add_u32_e32 v135, s2, v164
	v_ashrrev_i32_e32 v135, 2, v135
	v_med3_i32 v135, v135, 0, s14
	v_lshl_add_u32 v135, v135, 9, v178
	global_load_dwordx4 v[20:23], v135, s[86:87]
	s_add_i32 s2, s42, -16
	v_add_u32_e32 v136, s2, v164
	v_ashrrev_i32_e32 v136, 2, v136
	v_med3_i32 v136, v136, 0, s14
	v_lshl_add_u32 v136, v136, 9, v178
	global_load_dwordx4 v[24:27], v136, s[86:87]
	s_add_i32 s2, s42, -8
	v_add_u32_e32 v135, s2, v164
	v_ashrrev_i32_e32 v135, 2, v135
	v_med3_i32 v135, v135, 0, s14
	v_lshl_add_u32 v135, v135, 9, v178
	global_load_dwordx4 v[28:31], v135, s[86:87]
	s_add_i32 s2, s42, 0
	v_add_u32_e32 v136, s2, v164
	v_ashrrev_i32_e32 v136, 2, v136
	v_med3_i32 v136, v136, 0, s14
	v_lshl_add_u32 v136, v136, 9, v178
	global_load_dwordx4 v[32:35], v136, s[86:87]
	s_add_i32 s2, s42, 8
	v_add_u32_e32 v135, s2, v164
	v_ashrrev_i32_e32 v135, 2, v135
	v_med3_i32 v135, v135, 0, s14
	v_lshl_add_u32 v135, v135, 9, v178
	global_load_dwordx4 v[36:39], v135, s[86:87]
	s_add_i32 s2, s42, 16
	v_add_u32_e32 v136, s2, v164
	v_ashrrev_i32_e32 v136, 2, v136
	v_med3_i32 v136, v136, 0, s14
	v_lshl_add_u32 v136, v136, 9, v178
	global_load_dwordx4 v[40:43], v136, s[86:87]
	s_add_i32 s2, s42, 24
	v_add_u32_e32 v135, s2, v164
	v_ashrrev_i32_e32 v135, 2, v135
	v_med3_i32 v135, v135, 0, s14
	v_lshl_add_u32 v135, v135, 9, v178
	global_load_dwordx4 v[44:47], v135, s[86:87]
	s_lshl_b32 s2, s43, s13
	s_lshl_b32 s2, s2, 7
	s_add_u32 s74, s22, s2
	s_addc_u32 s75, s23, 0
	s_add_i32 s2, s42, -64
	v_add_u32_e32 v137, s2, v164
	v_ashrrev_i32_e32 v137, 2, v137
	v_med3_i32 v137, v137, 0, s14
	v_lshl_add_u32 v137, v137, 9, v178
	global_load_dwordx4 v[64:67], v137, s[74:75]
	s_add_i32 s2, s42, -56
	v_add_u32_e32 v137, s2, v164
	v_ashrrev_i32_e32 v137, 2, v137
	v_med3_i32 v137, v137, 0, s14
	v_lshl_add_u32 v137, v137, 9, v178
	global_load_dwordx4 v[68:71], v137, s[74:75]
	s_add_i32 s2, s42, -48
	v_add_u32_e32 v137, s2, v164
	v_ashrrev_i32_e32 v137, 2, v137
	v_med3_i32 v137, v137, 0, s14
	v_lshl_add_u32 v137, v137, 9, v178
	global_load_dwordx4 v[72:75], v137, s[74:75]
	s_add_i32 s2, s42, -40
	v_add_u32_e32 v137, s2, v164
	v_ashrrev_i32_e32 v137, 2, v137
	v_med3_i32 v137, v137, 0, s14
	v_lshl_add_u32 v137, v137, 9, v178
	global_load_dwordx4 v[76:79], v137, s[74:75]
	s_lshl_b32 s2, s43, s13
	s_lshl_b32 s2, s2, 7
	s_add_u32 s74, s22, s2
	s_addc_u32 s75, s23, 0
	s_add_i32 s2, s42, -32
	v_add_u32_e32 v137, s2, v164
	v_ashrrev_i32_e32 v137, 2, v137
	v_med3_i32 v137, v137, 0, s14
	v_lshl_add_u32 v137, v137, 9, v178
	global_load_dwordx4 v[80:83], v137, s[74:75]
	s_add_i32 s2, s42, -24
	v_add_u32_e32 v137, s2, v164
	v_ashrrev_i32_e32 v137, 2, v137
	v_med3_i32 v137, v137, 0, s14
	v_lshl_add_u32 v137, v137, 9, v178
	global_load_dwordx4 v[84:87], v137, s[74:75]
	s_add_i32 s2, s42, -16
	v_add_u32_e32 v137, s2, v164
	v_ashrrev_i32_e32 v137, 2, v137
	v_med3_i32 v137, v137, 0, s14
	v_lshl_add_u32 v137, v137, 9, v178
	global_load_dwordx4 v[88:91], v137, s[74:75]
	s_add_i32 s2, s42, -8
	v_add_u32_e32 v137, s2, v164
	v_ashrrev_i32_e32 v137, 2, v137
	v_med3_i32 v137, v137, 0, s14
	v_lshl_add_u32 v137, v137, 9, v178
	global_load_dwordx4 v[92:95], v137, s[74:75]
	s_lshl_b32 s2, s43, s13
	s_lshl_b32 s2, s2, 7
	s_add_u32 s74, s22, s2
	s_addc_u32 s75, s23, 0
	s_add_i32 s2, s42, 0
	v_add_u32_e32 v137, s2, v164
	v_ashrrev_i32_e32 v137, 2, v137
	v_med3_i32 v137, v137, 0, s14
	v_lshl_add_u32 v137, v137, 9, v178
	global_load_dwordx4 v[96:99], v137, s[74:75]
	s_add_i32 s2, s42, 8
	v_add_u32_e32 v137, s2, v164
	v_ashrrev_i32_e32 v137, 2, v137
	v_med3_i32 v137, v137, 0, s14
	v_lshl_add_u32 v137, v137, 9, v178
	global_load_dwordx4 v[100:103], v137, s[74:75]
	s_add_i32 s2, s42, 16
	v_add_u32_e32 v137, s2, v164
	v_ashrrev_i32_e32 v137, 2, v137
	v_med3_i32 v137, v137, 0, s14
	v_lshl_add_u32 v137, v137, 9, v178
	global_load_dwordx4 v[104:107], v137, s[74:75]
	s_add_i32 s2, s42, 24
	v_add_u32_e32 v137, s2, v164
	v_ashrrev_i32_e32 v137, 2, v137
	v_med3_i32 v137, v137, 0, s14
	v_lshl_add_u32 v137, v137, 9, v178
	global_load_dwordx4 v[108:111], v137, s[74:75]
	v_subrev_u32_e32 v143, s80, v174
	v_lshl_add_u32 v143, v143, 5, v161
	v_add_u32_e32 v143, 0x1b500, v143
	ds_read_b128 v[48:51], v143
	ds_read_b128 v[52:55], v143 offset:64
	ds_read_b128 v[56:59], v143 offset:2048
	ds_read_b128 v[60:63], v143 offset:2112
	s_waitcnt lgkmcnt(0)
	v_mov_b32_e32 v138, 0
	v_mov_b32_e32 v139, 0
	v_mov_b32_e32 v140, 0
	v_mov_b32_e32 v141, 0
	ds_read_b128 v[204:207], v149
	ds_read_b128 v[208:211], v149 offset:64
	ds_read_b128 v[212:215], v149 offset:2304
	ds_read_b128 v[216:219], v149 offset:2368
	ds_read_b128 v[220:223], v149 offset:4608
	ds_read_b128 v[224:227], v149 offset:4672
	ds_read_b128 v[228:231], v149 offset:6912
	ds_read_b128 v[232:235], v149 offset:6976
	s_waitcnt lgkmcnt(0)
	v_mfma_f32_16x16x32_bf16 v[236:239], v[204:207], v[48:51], 0
	v_mfma_f32_16x16x32_bf16 v[236:239], v[208:211], v[52:55], v[236:239]
	v_mfma_f32_16x16x32_bf16 v[240:243], v[212:215], v[48:51], 0
	v_mfma_f32_16x16x32_bf16 v[240:243], v[216:219], v[52:55], v[240:243]
	v_mfma_f32_16x16x32_bf16 v[248:251], v[212:215], v[56:59], 0
	v_mfma_f32_16x16x32_bf16 v[248:251], v[216:219], v[60:63], v[248:251]
	s_nop 7
	s_add_i32 s77, s40, -64
	s_cmp_lt_u32 s77, s44
	s_cselect_b32 s76, s70, s71
	v_min_f32_e32 v152, s76, v236
	v_min_f32_e32 v153, s76, v237
	v_min_f32_e32 v154, s76, v238
	v_min_f32_e32 v155, s76, v239
	v_mfma_f32_16x16x32_bf16 v[236:239], v[220:223], v[48:51], 0
	v_mfma_f32_16x16x32_bf16 v[236:239], v[224:227], v[52:55], v[236:239]
	v_mfma_f32_16x16x32_bf16 v[244:247], v[220:223], v[56:59], 0
	v_mfma_f32_16x16x32_bf16 v[244:247], v[224:227], v[60:63], v[244:247]
	ds_read_b128 v[204:207], v149 offset:9216
	ds_read_b128 v[208:211], v149 offset:9280
	v_pk_mul_f32 v[152:153], v[152:153], s[72:73]
	v_pk_mul_f32 v[154:155], v[154:155], s[72:73]
	v_exp_f32_e32 v152, v152
	v_exp_f32_e32 v153, v153
	v_exp_f32_e32 v154, v154
	v_exp_f32_e32 v155, v155
	v_cndmask_b32_e64 v152, 0, v152, s[54:55]
	v_cndmask_b32_e64 v153, 0, v153, s[56:57]
	v_cndmask_b32_e64 v154, 0, v154, s[58:59]
	v_cndmask_b32_e64 v155, 0, v155, s[60:61]
	v_pk_add_f32 v[138:139], v[138:139], v[152:153]
	v_pk_add_f32 v[138:139], v[138:139], v[154:155]
	v_cvt_pk_bf16_f32 v112, v152, v153
	v_cvt_pk_bf16_f32 v113, v154, v155
	s_add_i32 s77, s40, -48
	s_cmp_lt_u32 s77, s44
	s_cselect_b32 s76, s70, s71
	v_min_f32_e32 v152, s76, v240
	v_min_f32_e32 v153, s76, v241
	v_min_f32_e32 v154, s76, v242
	v_min_f32_e32 v155, s76, v243
	v_min_f32_e32 v156, s76, v248
	v_min_f32_e32 v157, s76, v249
	v_min_f32_e32 v158, s76, v250
	v_min_f32_e32 v159, s76, v251
	v_mfma_f32_16x16x32_bf16 v[240:243], v[228:231], v[48:51], 0
	v_mfma_f32_16x16x32_bf16 v[240:243], v[232:235], v[52:55], v[240:243]
	v_mfma_f32_16x16x32_bf16 v[248:251], v[228:231], v[56:59], 0
	v_mfma_f32_16x16x32_bf16 v[248:251], v[232:235], v[60:63], v[248:251]
	ds_read_b128 v[212:215], v149 offset:11520
	ds_read_b128 v[216:219], v149 offset:11584
	v_pk_mul_f32 v[152:153], v[152:153], s[72:73]
	v_pk_mul_f32 v[154:155], v[154:155], s[72:73]
	v_exp_f32_e32 v152, v152
	v_exp_f32_e32 v153, v153
	v_exp_f32_e32 v154, v154
	v_exp_f32_e32 v155, v155
	v_pk_add_f32 v[138:139], v[138:139], v[152:153]
	v_pk_add_f32 v[138:139], v[138:139], v[154:155]
	v_cvt_pk_bf16_f32 v114, v152, v153
	v_cvt_pk_bf16_f32 v115, v154, v155
	v_pk_mul_f32 v[156:157], v[156:157], s[72:73]
	v_pk_mul_f32 v[158:159], v[158:159], s[72:73]
	v_exp_f32_e32 v156, v156
	v_exp_f32_e32 v157, v157
	v_exp_f32_e32 v158, v158
	v_exp_f32_e32 v159, v159
	v_cndmask_b32_e64 v156, 0, v156, s[54:55]
	v_cndmask_b32_e64 v157, 0, v157, s[56:57]
	v_cndmask_b32_e64 v158, 0, v158, s[58:59]
	v_cndmask_b32_e64 v159, 0, v159, s[60:61]
	v_pk_add_f32 v[140:141], v[140:141], v[156:157]
	v_pk_add_f32 v[140:141], v[140:141], v[158:159]
	v_cvt_pk_bf16_f32 v186, v156, v157
	v_cvt_pk_bf16_f32 v187, v158, v159
	s_add_i32 s77, s40, -32
	s_cmp_lt_u32 s77, s44
	s_cselect_b32 s76, s70, s71
	v_min_f32_e32 v152, s76, v236
	v_min_f32_e32 v153, s76, v237
	v_min_f32_e32 v154, s76, v238
	v_min_f32_e32 v155, s76, v239
	v_min_f32_e32 v156, s76, v244
	v_min_f32_e32 v157, s76, v245
	v_min_f32_e32 v158, s76, v246
	v_min_f32_e32 v159, s76, v247
	s_waitcnt lgkmcnt(2)
	v_mfma_f32_16x16x32_bf16 v[236:239], v[204:207], v[48:51], 0
	v_mfma_f32_16x16x32_bf16 v[236:239], v[208:211], v[52:55], v[236:239]
	v_mfma_f32_16x16x32_bf16 v[244:247], v[204:207], v[56:59], 0
	v_mfma_f32_16x16x32_bf16 v[244:247], v[208:211], v[60:63], v[244:247]
	ds_read_b128 v[220:223], v149 offset:13824
	ds_read_b128 v[224:227], v149 offset:13888
	v_pk_mul_f32 v[152:153], v[152:153], s[72:73]
	v_pk_mul_f32 v[154:155], v[154:155], s[72:73]
	v_exp_f32_e32 v152, v152
	v_exp_f32_e32 v153, v153
	v_exp_f32_e32 v154, v154
	v_exp_f32_e32 v155, v155
	v_pk_add_f32 v[138:139], v[138:139], v[152:153]
	v_pk_add_f32 v[138:139], v[138:139], v[154:155]
	v_cvt_pk_bf16_f32 v116, v152, v153
	v_cvt_pk_bf16_f32 v117, v154, v155
	v_pk_mul_f32 v[156:157], v[156:157], s[72:73]
	v_pk_mul_f32 v[158:159], v[158:159], s[72:73]
	v_exp_f32_e32 v156, v156
	v_exp_f32_e32 v157, v157
	v_exp_f32_e32 v158, v158
	v_exp_f32_e32 v159, v159
	v_pk_add_f32 v[140:141], v[140:141], v[156:157]
	v_pk_add_f32 v[140:141], v[140:141], v[158:159]
	v_cvt_pk_bf16_f32 v188, v156, v157
	v_cvt_pk_bf16_f32 v189, v158, v159
	s_add_i32 s77, s40, -16
	s_cmp_lt_u32 s77, s44
	s_cselect_b32 s76, s70, s71
	v_min_f32_e32 v152, s76, v240
	v_min_f32_e32 v153, s76, v241
	v_min_f32_e32 v154, s76, v242
	v_min_f32_e32 v155, s76, v243
	v_min_f32_e32 v156, s76, v248
	v_min_f32_e32 v157, s76, v249
	v_min_f32_e32 v158, s76, v250
	v_min_f32_e32 v159, s76, v251
	s_waitcnt lgkmcnt(2)
	v_mfma_f32_16x16x32_bf16 v[240:243], v[212:215], v[48:51], 0
	v_mfma_f32_16x16x32_bf16 v[240:243], v[216:219], v[52:55], v[240:243]
	v_mfma_f32_16x16x32_bf16 v[248:251], v[212:215], v[56:59], 0
	v_mfma_f32_16x16x32_bf16 v[248:251], v[216:219], v[60:63], v[248:251]
	ds_read_b128 v[228:231], v149 offset:16128
	ds_read_b128 v[232:235], v149 offset:16192
	v_pk_mul_f32 v[152:153], v[152:153], s[72:73]
	v_pk_mul_f32 v[154:155], v[154:155], s[72:73]
	v_exp_f32_e32 v152, v152
	v_exp_f32_e32 v153, v153
	v_exp_f32_e32 v154, v154
	v_exp_f32_e32 v155, v155
	v_pk_add_f32 v[138:139], v[138:139], v[152:153]
	v_pk_add_f32 v[138:139], v[138:139], v[154:155]
	v_cvt_pk_bf16_f32 v118, v152, v153
	v_cvt_pk_bf16_f32 v119, v154, v155
	v_pk_mul_f32 v[156:157], v[156:157], s[72:73]
	v_pk_mul_f32 v[158:159], v[158:159], s[72:73]
	v_exp_f32_e32 v156, v156
	v_exp_f32_e32 v157, v157
	v_exp_f32_e32 v158, v158
	v_exp_f32_e32 v159, v159
	v_pk_add_f32 v[140:141], v[140:141], v[156:157]
	v_pk_add_f32 v[140:141], v[140:141], v[158:159]
	v_cvt_pk_bf16_f32 v190, v156, v157
	v_cvt_pk_bf16_f32 v191, v158, v159
	s_add_i32 s77, s40, 0
	s_cmp_lt_u32 s77, s44
	s_cselect_b32 s76, s70, s71
	v_min_f32_e32 v152, s76, v236
	v_min_f32_e32 v153, s76, v237
	v_min_f32_e32 v154, s76, v238
	v_min_f32_e32 v155, s76, v239
	v_min_f32_e32 v156, s76, v244
	v_min_f32_e32 v157, s76, v245
	v_min_f32_e32 v158, s76, v246
	v_min_f32_e32 v159, s76, v247
	s_waitcnt lgkmcnt(2)
	v_mfma_f32_16x16x32_bf16 v[236:239], v[220:223], v[48:51], 0
	v_mfma_f32_16x16x32_bf16 v[236:239], v[224:227], v[52:55], v[236:239]
	v_mfma_f32_16x16x32_bf16 v[244:247], v[220:223], v[56:59], 0
	v_mfma_f32_16x16x32_bf16 v[244:247], v[224:227], v[60:63], v[244:247]
	ds_read_b128 v[204:207], v149 offset:18432
	ds_read_b128 v[208:211], v149 offset:18496
	v_pk_mul_f32 v[152:153], v[152:153], s[72:73]
	v_pk_mul_f32 v[154:155], v[154:155], s[72:73]
	v_exp_f32_e32 v152, v152
	v_exp_f32_e32 v153, v153
	v_exp_f32_e32 v154, v154
	v_exp_f32_e32 v155, v155
	v_pk_add_f32 v[138:139], v[138:139], v[152:153]
	v_pk_add_f32 v[138:139], v[138:139], v[154:155]
	v_cvt_pk_bf16_f32 v120, v152, v153
	v_cvt_pk_bf16_f32 v121, v154, v155
	v_pk_mul_f32 v[156:157], v[156:157], s[72:73]
	v_pk_mul_f32 v[158:159], v[158:159], s[72:73]
	v_exp_f32_e32 v156, v156
	v_exp_f32_e32 v157, v157
	v_exp_f32_e32 v158, v158
	v_exp_f32_e32 v159, v159
	v_pk_add_f32 v[140:141], v[140:141], v[156:157]
	v_pk_add_f32 v[140:141], v[140:141], v[158:159]
	v_cvt_pk_bf16_f32 v192, v156, v157
	v_cvt_pk_bf16_f32 v193, v158, v159
	s_add_i32 s77, s40, 16
	s_cmp_lt_u32 s77, s44
	s_cselect_b32 s76, s70, s71
	v_min_f32_e32 v152, s76, v240
	v_min_f32_e32 v153, s76, v241
	v_min_f32_e32 v154, s76, v242
	v_min_f32_e32 v155, s76, v243
	v_min_f32_e32 v156, s76, v248
	v_min_f32_e32 v157, s76, v249
	v_min_f32_e32 v158, s76, v250
	v_min_f32_e32 v159, s76, v251
	s_waitcnt lgkmcnt(2)
	v_mfma_f32_16x16x32_bf16 v[240:243], v[228:231], v[48:51], 0
	v_mfma_f32_16x16x32_bf16 v[240:243], v[232:235], v[52:55], v[240:243]
	v_mfma_f32_16x16x32_bf16 v[248:251], v[228:231], v[56:59], 0
	v_mfma_f32_16x16x32_bf16 v[248:251], v[232:235], v[60:63], v[248:251]
	ds_read_b128 v[212:215], v149 offset:20736
	ds_read_b128 v[216:219], v149 offset:20800
	v_pk_mul_f32 v[152:153], v[152:153], s[72:73]
	v_pk_mul_f32 v[154:155], v[154:155], s[72:73]
	v_exp_f32_e32 v152, v152
	v_exp_f32_e32 v153, v153
	v_exp_f32_e32 v154, v154
	v_exp_f32_e32 v155, v155
	v_pk_add_f32 v[138:139], v[138:139], v[152:153]
	v_pk_add_f32 v[138:139], v[138:139], v[154:155]
	v_cvt_pk_bf16_f32 v122, v152, v153
	v_cvt_pk_bf16_f32 v123, v154, v155
	v_pk_mul_f32 v[156:157], v[156:157], s[72:73]
	v_pk_mul_f32 v[158:159], v[158:159], s[72:73]
	v_exp_f32_e32 v156, v156
	v_exp_f32_e32 v157, v157
	v_exp_f32_e32 v158, v158
	v_exp_f32_e32 v159, v159
	v_pk_add_f32 v[140:141], v[140:141], v[156:157]
	v_pk_add_f32 v[140:141], v[140:141], v[158:159]
	v_cvt_pk_bf16_f32 v194, v156, v157
	v_cvt_pk_bf16_f32 v195, v158, v159
	s_add_i32 s77, s40, 32
	s_cmp_lt_u32 s77, s44
	s_cselect_b32 s76, s70, s71
	v_min_f32_e32 v152, s76, v236
	v_min_f32_e32 v153, s76, v237
	v_min_f32_e32 v154, s76, v238
	v_min_f32_e32 v155, s76, v239
	v_min_f32_e32 v156, s76, v244
	v_min_f32_e32 v157, s76, v245
	v_min_f32_e32 v158, s76, v246
	v_min_f32_e32 v159, s76, v247
	s_waitcnt lgkmcnt(2)
	v_mfma_f32_16x16x32_bf16 v[236:239], v[204:207], v[48:51], 0
	v_mfma_f32_16x16x32_bf16 v[236:239], v[208:211], v[52:55], v[236:239]
	v_mfma_f32_16x16x32_bf16 v[244:247], v[204:207], v[56:59], 0
	v_mfma_f32_16x16x32_bf16 v[244:247], v[208:211], v[60:63], v[244:247]
	v_pk_mul_f32 v[152:153], v[152:153], s[72:73]
	v_pk_mul_f32 v[154:155], v[154:155], s[72:73]
	v_exp_f32_e32 v152, v152
	v_exp_f32_e32 v153, v153
	v_exp_f32_e32 v154, v154
	v_exp_f32_e32 v155, v155
	v_pk_add_f32 v[138:139], v[138:139], v[152:153]
	v_pk_add_f32 v[138:139], v[138:139], v[154:155]
	v_cvt_pk_bf16_f32 v124, v152, v153
	v_cvt_pk_bf16_f32 v125, v154, v155
	v_pk_mul_f32 v[156:157], v[156:157], s[72:73]
	v_pk_mul_f32 v[158:159], v[158:159], s[72:73]
	v_exp_f32_e32 v156, v156
	v_exp_f32_e32 v157, v157
	v_exp_f32_e32 v158, v158
	v_exp_f32_e32 v159, v159
	v_pk_add_f32 v[140:141], v[140:141], v[156:157]
	v_pk_add_f32 v[140:141], v[140:141], v[158:159]
	v_cvt_pk_bf16_f32 v196, v156, v157
	v_cvt_pk_bf16_f32 v197, v158, v159
	s_add_i32 s77, s40, 48
	s_cmp_lt_u32 s77, s44
	s_cselect_b32 s76, s70, s71
	v_min_f32_e32 v152, s76, v240
	v_min_f32_e32 v153, s76, v241
	v_min_f32_e32 v154, s76, v242
	v_min_f32_e32 v155, s76, v243
	v_min_f32_e32 v156, s76, v248
	v_min_f32_e32 v157, s76, v249
	v_min_f32_e32 v158, s76, v250
	v_min_f32_e32 v159, s76, v251
	s_waitcnt lgkmcnt(0)
	v_mfma_f32_16x16x32_bf16 v[248:251], v[212:215], v[56:59], 0
	v_mfma_f32_16x16x32_bf16 v[248:251], v[216:219], v[60:63], v[248:251]
	v_pk_mul_f32 v[152:153], v[152:153], s[72:73]
	v_pk_mul_f32 v[154:155], v[154:155], s[72:73]
	v_exp_f32_e32 v152, v152
	v_exp_f32_e32 v153, v153
	v_exp_f32_e32 v154, v154
	v_exp_f32_e32 v155, v155
	v_pk_add_f32 v[138:139], v[138:139], v[152:153]
	v_pk_add_f32 v[138:139], v[138:139], v[154:155]
	v_cvt_pk_bf16_f32 v126, v152, v153
	v_cvt_pk_bf16_f32 v127, v154, v155
	v_pk_mul_f32 v[156:157], v[156:157], s[72:73]
	v_pk_mul_f32 v[158:159], v[158:159], s[72:73]
	v_exp_f32_e32 v156, v156
	v_exp_f32_e32 v157, v157
	v_exp_f32_e32 v158, v158
	v_exp_f32_e32 v159, v159
	v_pk_add_f32 v[140:141], v[140:141], v[156:157]
	v_pk_add_f32 v[140:141], v[140:141], v[158:159]
	v_cvt_pk_bf16_f32 v198, v156, v157
	v_cvt_pk_bf16_f32 v199, v158, v159
	s_add_i32 s77, s40, 64
	s_cmp_lt_u32 s77, s44
	s_cselect_b32 s76, s70, s71
	v_min_f32_e32 v152, s76, v236
	v_min_f32_e32 v153, s76, v237
	v_min_f32_e32 v154, s76, v238
	v_min_f32_e32 v155, s76, v239
	v_min_f32_e32 v156, s76, v244
	v_min_f32_e32 v157, s76, v245
	v_min_f32_e32 v158, s76, v246
	v_min_f32_e32 v159, s76, v247
	v_pk_mul_f32 v[152:153], v[152:153], s[72:73]
	v_pk_mul_f32 v[154:155], v[154:155], s[72:73]
	v_exp_f32_e32 v152, v152
	v_exp_f32_e32 v153, v153
	v_exp_f32_e32 v154, v154
	v_exp_f32_e32 v155, v155
	v_cndmask_b32_e64 v152, 0, v152, s[62:63]
	v_cndmask_b32_e64 v153, 0, v153, s[64:65]
	v_cndmask_b32_e64 v154, 0, v154, s[66:67]
	v_cndmask_b32_e64 v155, 0, v155, s[68:69]
	v_pk_add_f32 v[138:139], v[138:139], v[152:153]
	v_pk_add_f32 v[138:139], v[138:139], v[154:155]
	v_cvt_pk_bf16_f32 v128, v152, v153
	v_cvt_pk_bf16_f32 v129, v154, v155
	v_pk_mul_f32 v[156:157], v[156:157], s[72:73]
	v_pk_mul_f32 v[158:159], v[158:159], s[72:73]
	v_exp_f32_e32 v156, v156
	v_exp_f32_e32 v157, v157
	v_exp_f32_e32 v158, v158
	v_exp_f32_e32 v159, v159
	v_pk_add_f32 v[140:141], v[140:141], v[156:157]
	v_pk_add_f32 v[140:141], v[140:141], v[158:159]
	v_cvt_pk_bf16_f32 v200, v156, v157
	v_cvt_pk_bf16_f32 v201, v158, v159
	s_add_i32 s77, s40, 80
	s_cmp_lt_u32 s77, s44
	s_cselect_b32 s76, s70, s71
	v_min_f32_e32 v156, s76, v248
	v_min_f32_e32 v157, s76, v249
	v_min_f32_e32 v158, s76, v250
	v_min_f32_e32 v159, s76, v251
	v_pk_mul_f32 v[156:157], v[156:157], s[72:73]
	v_pk_mul_f32 v[158:159], v[158:159], s[72:73]
	v_exp_f32_e32 v156, v156
	v_exp_f32_e32 v157, v157
	v_exp_f32_e32 v158, v158
	v_exp_f32_e32 v159, v159
	v_cndmask_b32_e64 v156, 0, v156, s[62:63]
	v_cndmask_b32_e64 v157, 0, v157, s[64:65]
	v_cndmask_b32_e64 v158, 0, v158, s[66:67]
	v_cndmask_b32_e64 v159, 0, v159, s[68:69]
	v_pk_add_f32 v[140:141], v[140:141], v[156:157]
	v_pk_add_f32 v[140:141], v[140:141], v[158:159]
	v_cvt_pk_bf16_f32 v202, v156, v157
	v_cvt_pk_bf16_f32 v203, v158, v159
	v_add_f32_e32 v132, v138, v139
	v_add_f32_e32 v133, v140, v141
	ds_bpermute_b32 v142, v167, v132
	s_waitcnt lgkmcnt(0)
	v_add_f32_e32 v132, v132, v142
	ds_bpermute_b32 v142, v168, v132
	s_waitcnt lgkmcnt(0)
	v_add_f32_e32 v132, v132, v142
	ds_bpermute_b32 v142, v167, v133
	s_waitcnt lgkmcnt(0)
	v_add_f32_e32 v133, v133, v142
	ds_bpermute_b32 v142, v168, v133
	s_waitcnt lgkmcnt(0)
	v_add_f32_e32 v133, v133, v142
	ds_read_b64_tr_b16 v[236:237], v151 offset:0
	ds_read_b64_tr_b16 v[238:239], v151 offset:2304
	ds_read_b64_tr_b16 v[240:241], v151 offset:32
	ds_read_b64_tr_b16 v[242:243], v151 offset:2336
	ds_read_b64_tr_b16 v[244:245], v151 offset:64
	ds_read_b64_tr_b16 v[246:247], v151 offset:2368
	ds_read_b64_tr_b16 v[248:249], v151 offset:96
	ds_read_b64_tr_b16 v[250:251], v151 offset:2400
	s_waitcnt lgkmcnt(0)
	v_mfma_f32_16x16x32_bf16 v[204:207], v[236:239], v[112:115], 0
	v_mfma_f32_16x16x32_bf16 v[208:211], v[240:243], v[112:115], 0
	v_mfma_f32_16x16x32_bf16 v[212:215], v[244:247], v[112:115], 0
	v_mfma_f32_16x16x32_bf16 v[216:219], v[248:251], v[112:115], 0
	v_mfma_f32_16x16x32_bf16 v[220:223], v[236:239], v[184:187], 0
	v_mfma_f32_16x16x32_bf16 v[224:227], v[240:243], v[184:187], 0
	v_mfma_f32_16x16x32_bf16 v[228:231], v[244:247], v[184:187], 0
	v_mfma_f32_16x16x32_bf16 v[232:235], v[248:251], v[184:187], 0
	s_nop 7
	ds_read_b64_tr_b16 v[236:237], v151 offset:4608
	ds_read_b64_tr_b16 v[238:239], v151 offset:6912
	ds_read_b64_tr_b16 v[240:241], v151 offset:4640
	ds_read_b64_tr_b16 v[242:243], v151 offset:6944
	ds_read_b64_tr_b16 v[244:245], v151 offset:4672
	ds_read_b64_tr_b16 v[246:247], v151 offset:6976
	ds_read_b64_tr_b16 v[248:249], v151 offset:4704
	ds_read_b64_tr_b16 v[250:251], v151 offset:7008
	s_waitcnt lgkmcnt(0)
	v_mfma_f32_16x16x32_bf16 v[204:207], v[236:239], v[116:119], v[204:207]
	v_mfma_f32_16x16x32_bf16 v[208:211], v[240:243], v[116:119], v[208:211]
	v_mfma_f32_16x16x32_bf16 v[212:215], v[244:247], v[116:119], v[212:215]
	v_mfma_f32_16x16x32_bf16 v[216:219], v[248:251], v[116:119], v[216:219]
	v_mfma_f32_16x16x32_bf16 v[220:223], v[236:239], v[188:191], v[220:223]
	v_mfma_f32_16x16x32_bf16 v[224:227], v[240:243], v[188:191], v[224:227]
	v_mfma_f32_16x16x32_bf16 v[228:231], v[244:247], v[188:191], v[228:231]
	v_mfma_f32_16x16x32_bf16 v[232:235], v[248:251], v[188:191], v[232:235]
	s_nop 7
	ds_read_b64_tr_b16 v[236:237], v151 offset:9216
	ds_read_b64_tr_b16 v[238:239], v151 offset:11520
	ds_read_b64_tr_b16 v[240:241], v151 offset:9248
	ds_read_b64_tr_b16 v[242:243], v151 offset:11552
	ds_read_b64_tr_b16 v[244:245], v151 offset:9280
	ds_read_b64_tr_b16 v[246:247], v151 offset:11584
	ds_read_b64_tr_b16 v[248:249], v151 offset:9312
	ds_read_b64_tr_b16 v[250:251], v151 offset:11616
	s_waitcnt lgkmcnt(0)
	v_mfma_f32_16x16x32_bf16 v[204:207], v[236:239], v[120:123], v[204:207]
	v_mfma_f32_16x16x32_bf16 v[208:211], v[240:243], v[120:123], v[208:211]
	v_mfma_f32_16x16x32_bf16 v[212:215], v[244:247], v[120:123], v[212:215]
	v_mfma_f32_16x16x32_bf16 v[216:219], v[248:251], v[120:123], v[216:219]
	v_mfma_f32_16x16x32_bf16 v[220:223], v[236:239], v[192:195], v[220:223]
	v_mfma_f32_16x16x32_bf16 v[224:227], v[240:243], v[192:195], v[224:227]
	v_mfma_f32_16x16x32_bf16 v[228:231], v[244:247], v[192:195], v[228:231]
	v_mfma_f32_16x16x32_bf16 v[232:235], v[248:251], v[192:195], v[232:235]
	s_nop 7
	ds_read_b64_tr_b16 v[236:237], v151 offset:13824
	ds_read_b64_tr_b16 v[238:239], v151 offset:16128
	ds_read_b64_tr_b16 v[240:241], v151 offset:13856
	ds_read_b64_tr_b16 v[242:243], v151 offset:16160
	ds_read_b64_tr_b16 v[244:245], v151 offset:13888
	ds_read_b64_tr_b16 v[246:247], v151 offset:16192
	ds_read_b64_tr_b16 v[248:249], v151 offset:13920
	ds_read_b64_tr_b16 v[250:251], v151 offset:16224
	s_waitcnt lgkmcnt(0)
	v_mfma_f32_16x16x32_bf16 v[204:207], v[236:239], v[124:127], v[204:207]
	v_mfma_f32_16x16x32_bf16 v[208:211], v[240:243], v[124:127], v[208:211]
	v_mfma_f32_16x16x32_bf16 v[212:215], v[244:247], v[124:127], v[212:215]
	v_mfma_f32_16x16x32_bf16 v[216:219], v[248:251], v[124:127], v[216:219]
	v_mfma_f32_16x16x32_bf16 v[220:223], v[236:239], v[196:199], v[220:223]
	v_mfma_f32_16x16x32_bf16 v[224:227], v[240:243], v[196:199], v[224:227]
	v_mfma_f32_16x16x32_bf16 v[228:231], v[244:247], v[196:199], v[228:231]
	v_mfma_f32_16x16x32_bf16 v[232:235], v[248:251], v[196:199], v[232:235]
	s_nop 7
	ds_read_b64_tr_b16 v[236:237], v151 offset:18432
	ds_read_b64_tr_b16 v[238:239], v151 offset:20736
	ds_read_b64_tr_b16 v[240:241], v151 offset:18464
	ds_read_b64_tr_b16 v[242:243], v151 offset:20768
	ds_read_b64_tr_b16 v[244:245], v151 offset:18496
	ds_read_b64_tr_b16 v[246:247], v151 offset:20800
	ds_read_b64_tr_b16 v[248:249], v151 offset:18528
	ds_read_b64_tr_b16 v[250:251], v151 offset:20832
	s_waitcnt lgkmcnt(0)
	v_mfma_f32_16x16x32_bf16 v[204:207], v[236:239], v[128:131], v[204:207]
	v_mfma_f32_16x16x32_bf16 v[208:211], v[240:243], v[128:131], v[208:211]
	v_mfma_f32_16x16x32_bf16 v[212:215], v[244:247], v[128:131], v[212:215]
	v_mfma_f32_16x16x32_bf16 v[216:219], v[248:251], v[128:131], v[216:219]
	v_mfma_f32_16x16x32_bf16 v[220:223], v[236:239], v[200:203], v[220:223]
	v_mfma_f32_16x16x32_bf16 v[224:227], v[240:243], v[200:203], v[224:227]
	v_mfma_f32_16x16x32_bf16 v[228:231], v[244:247], v[200:203], v[228:231]
	v_mfma_f32_16x16x32_bf16 v[232:235], v[248:251], v[200:203], v[232:235]
	s_barrier
	s_add_i32 s2, s42, 32
	v_add_u32_e32 v136, s2, v164
	v_ashrrev_i32_e32 v136, 2, v136
	v_med3_i32 v136, v136, 0, s14
	v_lshl_add_u32 v136, v136, 9, v178
	global_load_dwordx4 v[120:123], v136, s[86:87]
	s_add_i32 s2, s42, 40
	v_add_u32_e32 v135, s2, v164
	v_ashrrev_i32_e32 v135, 2, v135
	v_med3_i32 v135, v135, 0, s14
	v_lshl_add_u32 v135, v135, 9, v178
	global_load_dwordx4 v[124:127], v135, s[86:87]
	s_add_i32 s2, s42, 48
	v_add_u32_e32 v136, s2, v164
	v_ashrrev_i32_e32 v136, 2, v136
	v_med3_i32 v136, v136, 0, s14
	v_lshl_add_u32 v136, v136, 9, v178
	global_load_dwordx4 v[192:195], v136, s[86:87]
	s_add_i32 s2, s42, 56
	v_add_u32_e32 v135, s2, v164
	v_ashrrev_i32_e32 v135, 2, v135
	v_med3_i32 v135, v135, 0, s14
	v_lshl_add_u32 v135, v135, 9, v178
	global_load_dwordx4 v[196:199], v135, s[86:87]
	ds_write_b128 v173, v[204:207] offset:0
	ds_write_b128 v173, v[208:211] offset:64
	ds_write_b128 v173, v[212:215] offset:128
	ds_write_b128 v173, v[216:219] offset:192
	ds_write_b32 v174, v132 offset:0
	ds_write_b128 v173, v[220:223] offset:4624
	ds_write_b128 v173, v[224:227] offset:4688
	ds_write_b128 v173, v[228:231] offset:4752
	ds_write_b128 v173, v[232:235] offset:4816
	ds_write_b32 v174, v133 offset:64
	s_waitcnt lgkmcnt(0)
	s_barrier
	s_mov_b32 s40, s42
	s_mov_b32 s41, s43
	v_mov_b32_e32 v173, v176
	v_mov_b32_e32 v174, v177
	s_lshr_b32 s44, s33, 2
	s_lshr_b32 s42, s15, 4
	s_add_i32 s43, s0, 0
	v_subrev_u32_e32 v143, s80, v174
	v_lshl_add_u32 v143, v143, 5, v161
	v_add_u32_e32 v143, 0x1b500, v143
	ds_read_b128 v[48:51], v143
	ds_read_b128 v[52:55], v143 offset:64
	ds_read_b128 v[56:59], v143 offset:8192
	ds_read_b128 v[60:63], v143 offset:8256
	s_waitcnt lgkmcnt(0)
	v_mov_b32_e32 v138, 0
	v_mov_b32_e32 v139, 0
	v_mov_b32_e32 v140, 0
	v_mov_b32_e32 v141, 0
	s_waitcnt vmcnt(24)
	ds_write_b128 v165, v[0:3]
	ds_write_b128 v165, v[4:7] offset:1152
	ds_write_b128 v165, v[8:11] offset:2304
	ds_write_b128 v165, v[12:15] offset:3456
	s_waitcnt lgkmcnt(0)
	ds_read_b128 v[204:207], v175
	ds_read_b128 v[208:211], v175 offset:64
	ds_read_b128 v[212:215], v175 offset:2304
	ds_read_b128 v[216:219], v175 offset:2368
	s_lshl_b32 s2, s41, s39
	s_lshl_b32 s2, s2, 7
	s_add_u32 s86, s24, s2
	s_addc_u32 s87, s25, 0
	s_add_i32 s2, s40, 64
	v_add_u32_e32 v136, s2, v164
	v_ashrrev_i32_e32 v136, 2, v136
	v_med3_i32 v136, v136, 0, s38
	v_lshl_add_u32 v136, v136, 9, v178
	global_load_dwordx4 v[0:3], v136, s[86:87]
	s_add_i32 s2, s40, 72
	v_add_u32_e32 v135, s2, v164
	v_ashrrev_i32_e32 v135, 2, v135
	v_med3_i32 v135, v135, 0, s38
	v_lshl_add_u32 v135, v135, 9, v178
	global_load_dwordx4 v[4:7], v135, s[86:87]
	s_add_i32 s2, s40, 80
	v_add_u32_e32 v136, s2, v164
	v_ashrrev_i32_e32 v136, 2, v136
	v_med3_i32 v136, v136, 0, s38
	v_lshl_add_u32 v136, v136, 9, v178
	global_load_dwordx4 v[8:11], v136, s[86:87]
	s_add_i32 s2, s40, 88
	v_add_u32_e32 v135, s2, v164
	v_ashrrev_i32_e32 v135, 2, v135
	v_med3_i32 v135, v135, 0, s38
	v_lshl_add_u32 v135, v135, 9, v178
	global_load_dwordx4 v[12:15], v135, s[86:87]
	s_waitcnt vmcnt(24)
	s_waitcnt lgkmcnt(0)
	ds_write_b128 v165, v[16:19]
	ds_write_b128 v165, v[20:23] offset:1152
	ds_write_b128 v165, v[24:27] offset:2304
	ds_write_b128 v165, v[28:31] offset:3456
	v_mfma_f32_16x16x32_bf16 v[236:239], v[204:207], v[48:51], 0
	v_mfma_f32_16x16x32_bf16 v[236:239], v[208:211], v[52:55], v[236:239]
	v_mfma_f32_16x16x32_bf16 v[240:243], v[212:215], v[48:51], 0
	v_mfma_f32_16x16x32_bf16 v[240:243], v[216:219], v[52:55], v[240:243]
	v_mfma_f32_16x16x32_bf16 v[248:251], v[212:215], v[56:59], 0
	v_mfma_f32_16x16x32_bf16 v[248:251], v[216:219], v[60:63], v[248:251]
	s_waitcnt lgkmcnt(0)
	ds_read_b128 v[220:223], v175
	ds_read_b128 v[224:227], v175 offset:64
	s_lshl_b32 s2, s41, s39
	s_lshl_b32 s2, s2, 7
	s_add_u32 s74, s26, s2
	s_addc_u32 s75, s27, 0
	s_add_i32 s2, s40, 32
	v_add_u32_e32 v137, s2, v164
	v_ashrrev_i32_e32 v137, 2, v137
	v_med3_i32 v137, v137, 0, s38
	v_lshl_add_u32 v137, v137, 9, v178
	global_load_dwordx4 v[16:19], v137, s[74:75]
	s_add_i32 s2, s40, 40
	v_add_u32_e32 v137, s2, v164
	v_ashrrev_i32_e32 v137, 2, v137
	v_med3_i32 v137, v137, 0, s38
	v_lshl_add_u32 v137, v137, 9, v178
	global_load_dwordx4 v[20:23], v137, s[74:75]
	s_add_i32 s2, s40, 48
	v_add_u32_e32 v137, s2, v164
	v_ashrrev_i32_e32 v137, 2, v137
	v_med3_i32 v137, v137, 0, s38
	v_lshl_add_u32 v137, v137, 9, v178
	global_load_dwordx4 v[24:27], v137, s[74:75]
	s_add_i32 s2, s40, 56
	v_add_u32_e32 v137, s2, v164
	v_ashrrev_i32_e32 v137, 2, v137
	v_med3_i32 v137, v137, 0, s38
	v_lshl_add_u32 v137, v137, 9, v178
	global_load_dwordx4 v[28:31], v137, s[74:75]
	s_nop 7
	s_add_i32 s77, s40, -64
	s_cmp_lt_u32 s77, s44
	s_cselect_b32 s76, s70, s71
	v_min_f32_e32 v152, s76, v236
	v_min_f32_e32 v153, s76, v237
	v_min_f32_e32 v154, s76, v238
	v_min_f32_e32 v155, s76, v239
	s_waitcnt lgkmcnt(0)
	v_mfma_f32_16x16x32_bf16 v[236:239], v[220:223], v[48:51], 0
	v_mfma_f32_16x16x32_bf16 v[236:239], v[224:227], v[52:55], v[236:239]
	v_mfma_f32_16x16x32_bf16 v[244:247], v[220:223], v[56:59], 0
	v_mfma_f32_16x16x32_bf16 v[244:247], v[224:227], v[60:63], v[244:247]
	s_waitcnt vmcnt(26)
	ds_write_b128 v165, v[32:35]
	ds_write_b128 v165, v[36:39] offset:1152
	ds_read_b128 v[228:231], v175 offset:2304
	ds_read_b128 v[232:235], v175 offset:2368
	v_pk_mul_f32 v[152:153], v[152:153], s[72:73]
	v_pk_mul_f32 v[154:155], v[154:155], s[72:73]
	v_exp_f32_e32 v152, v152
	v_exp_f32_e32 v153, v153
	v_exp_f32_e32 v154, v154
	v_exp_f32_e32 v155, v155
	v_cndmask_b32_e64 v152, 0, v152, s[54:55]
	v_cndmask_b32_e64 v153, 0, v153, s[56:57]
	v_cndmask_b32_e64 v154, 0, v154, s[58:59]
	v_cndmask_b32_e64 v155, 0, v155, s[60:61]
	v_pk_add_f32 v[138:139], v[138:139], v[152:153]
	v_pk_add_f32 v[138:139], v[138:139], v[154:155]
	v_cvt_pk_bf16_f32 v112, v152, v153
	v_cvt_pk_bf16_f32 v113, v154, v155
	s_add_i32 s77, s40, -48
	s_cmp_lt_u32 s77, s44
	s_cselect_b32 s76, s70, s71
	v_min_f32_e32 v152, s76, v240
	v_min_f32_e32 v153, s76, v241
	v_min_f32_e32 v154, s76, v242
	v_min_f32_e32 v155, s76, v243
	v_min_f32_e32 v156, s76, v248
	v_min_f32_e32 v157, s76, v249
	v_min_f32_e32 v158, s76, v250
	v_min_f32_e32 v159, s76, v251
	s_waitcnt lgkmcnt(0)
	v_mfma_f32_16x16x32_bf16 v[240:243], v[228:231], v[48:51], 0
	v_mfma_f32_16x16x32_bf16 v[240:243], v[232:235], v[52:55], v[240:243]
	v_mfma_f32_16x16x32_bf16 v[248:251], v[228:231], v[56:59], 0
	v_mfma_f32_16x16x32_bf16 v[248:251], v[232:235], v[60:63], v[248:251]
	s_waitcnt vmcnt(24)
	ds_write_b128 v165, v[40:43] offset:2304
	ds_write_b128 v165, v[44:47] offset:3456
	ds_read_b128 v[204:207], v175
	ds_read_b128 v[208:211], v175 offset:64
	v_pk_mul_f32 v[152:153], v[152:153], s[72:73]
	v_pk_mul_f32 v[154:155], v[154:155], s[72:73]
	v_exp_f32_e32 v152, v152
	v_exp_f32_e32 v153, v153
	v_exp_f32_e32 v154, v154
	v_exp_f32_e32 v155, v155
	v_pk_add_f32 v[138:139], v[138:139], v[152:153]
	v_pk_add_f32 v[138:139], v[138:139], v[154:155]
	v_cvt_pk_bf16_f32 v114, v152, v153
	v_cvt_pk_bf16_f32 v115, v154, v155
	v_pk_mul_f32 v[156:157], v[156:157], s[72:73]
	v_pk_mul_f32 v[158:159], v[158:159], s[72:73]
	v_exp_f32_e32 v156, v156
	v_exp_f32_e32 v157, v157
	v_exp_f32_e32 v158, v158
	v_exp_f32_e32 v159, v159
	v_cndmask_b32_e64 v156, 0, v156, s[54:55]
	v_cndmask_b32_e64 v157, 0, v157, s[56:57]
	v_cndmask_b32_e64 v158, 0, v158, s[58:59]
	v_cndmask_b32_e64 v159, 0, v159, s[60:61]
	v_pk_add_f32 v[140:141], v[140:141], v[156:157]
	v_pk_add_f32 v[140:141], v[140:141], v[158:159]
	v_cvt_pk_bf16_f32 v186, v156, v157
	v_cvt_pk_bf16_f32 v187, v158, v159
	s_add_i32 s77, s40, -32
	s_cmp_lt_u32 s77, s44
	s_cselect_b32 s76, s70, s71
	v_min_f32_e32 v152, s76, v236
	v_min_f32_e32 v153, s76, v237
	v_min_f32_e32 v154, s76, v238
	v_min_f32_e32 v155, s76, v239
	v_min_f32_e32 v156, s76, v244
	v_min_f32_e32 v157, s76, v245
	v_min_f32_e32 v158, s76, v246
	v_min_f32_e32 v159, s76, v247
	s_waitcnt lgkmcnt(0)
	v_mfma_f32_16x16x32_bf16 v[236:239], v[204:207], v[48:51], 0
	v_mfma_f32_16x16x32_bf16 v[236:239], v[208:211], v[52:55], v[236:239]
	v_mfma_f32_16x16x32_bf16 v[244:247], v[204:207], v[56:59], 0
	v_mfma_f32_16x16x32_bf16 v[244:247], v[208:211], v[60:63], v[244:247]
	s_lshl_b32 s2, s41, s39
	s_lshl_b32 s2, s2, 7
	s_add_u32 s74, s26, s2
	s_addc_u32 s75, s27, 0
	s_add_i32 s2, s40, 64
	v_add_u32_e32 v137, s2, v164
	v_ashrrev_i32_e32 v137, 2, v137
	v_med3_i32 v137, v137, 0, s38
	v_lshl_add_u32 v137, v137, 9, v178
	global_load_dwordx4 v[32:35], v137, s[74:75]
	s_add_i32 s2, s40, 72
	v_add_u32_e32 v137, s2, v164
	v_ashrrev_i32_e32 v137, 2, v137
	v_med3_i32 v137, v137, 0, s38
	v_lshl_add_u32 v137, v137, 9, v178
	global_load_dwordx4 v[36:39], v137, s[74:75]
	s_add_i32 s2, s40, 80
	v_add_u32_e32 v137, s2, v164
	v_ashrrev_i32_e32 v137, 2, v137
	v_med3_i32 v137, v137, 0, s38
	v_lshl_add_u32 v137, v137, 9, v178
	global_load_dwordx4 v[40:43], v137, s[74:75]
	s_add_i32 s2, s40, 88
	v_add_u32_e32 v137, s2, v164
	v_ashrrev_i32_e32 v137, 2, v137
	v_med3_i32 v137, v137, 0, s38
	v_lshl_add_u32 v137, v137, 9, v178
	global_load_dwordx4 v[44:47], v137, s[74:75]
	s_waitcnt vmcnt(14)
	ds_write_b128 v165, v[120:123]
	ds_write_b128 v165, v[124:127] offset:1152
	ds_read_b128 v[212:215], v175 offset:2304
	ds_read_b128 v[216:219], v175 offset:2368
	v_pk_mul_f32 v[152:153], v[152:153], s[72:73]
	v_pk_mul_f32 v[154:155], v[154:155], s[72:73]
	v_exp_f32_e32 v152, v152
	v_exp_f32_e32 v153, v153
	v_exp_f32_e32 v154, v154
	v_exp_f32_e32 v155, v155
	v_pk_add_f32 v[138:139], v[138:139], v[152:153]
	v_pk_add_f32 v[138:139], v[138:139], v[154:155]
	v_cvt_pk_bf16_f32 v116, v152, v153
	v_cvt_pk_bf16_f32 v117, v154, v155
	v_pk_mul_f32 v[156:157], v[156:157], s[72:73]
	v_pk_mul_f32 v[158:159], v[158:159], s[72:73]
	v_exp_f32_e32 v156, v156
	v_exp_f32_e32 v157, v157
	v_exp_f32_e32 v158, v158
	v_exp_f32_e32 v159, v159
	v_pk_add_f32 v[140:141], v[140:141], v[156:157]
	v_pk_add_f32 v[140:141], v[140:141], v[158:159]
	v_cvt_pk_bf16_f32 v188, v156, v157
	v_cvt_pk_bf16_f32 v189, v158, v159
	s_add_i32 s77, s40, -16
	s_cmp_lt_u32 s77, s44
	s_cselect_b32 s76, s70, s71
	v_min_f32_e32 v152, s76, v240
	v_min_f32_e32 v153, s76, v241
	v_min_f32_e32 v154, s76, v242
	v_min_f32_e32 v155, s76, v243
	v_min_f32_e32 v156, s76, v248
	v_min_f32_e32 v157, s76, v249
	v_min_f32_e32 v158, s76, v250
	v_min_f32_e32 v159, s76, v251
	s_waitcnt lgkmcnt(0)
	v_mfma_f32_16x16x32_bf16 v[240:243], v[212:215], v[48:51], 0
	v_mfma_f32_16x16x32_bf16 v[240:243], v[216:219], v[52:55], v[240:243]
	v_mfma_f32_16x16x32_bf16 v[248:251], v[212:215], v[56:59], 0
	v_mfma_f32_16x16x32_bf16 v[248:251], v[216:219], v[60:63], v[248:251]
	s_waitcnt vmcnt(12)
	ds_write_b128 v165, v[192:195] offset:2304
	ds_write_b128 v165, v[196:199] offset:3456
	ds_read_b128 v[220:223], v175
	ds_read_b128 v[224:227], v175 offset:64
	v_pk_mul_f32 v[152:153], v[152:153], s[72:73]
	v_pk_mul_f32 v[154:155], v[154:155], s[72:73]
	v_exp_f32_e32 v152, v152
	v_exp_f32_e32 v153, v153
	v_exp_f32_e32 v154, v154
	v_exp_f32_e32 v155, v155
	v_pk_add_f32 v[138:139], v[138:139], v[152:153]
	v_pk_add_f32 v[138:139], v[138:139], v[154:155]
	v_cvt_pk_bf16_f32 v118, v152, v153
	v_cvt_pk_bf16_f32 v119, v154, v155
	v_pk_mul_f32 v[156:157], v[156:157], s[72:73]
	v_pk_mul_f32 v[158:159], v[158:159], s[72:73]
	v_exp_f32_e32 v156, v156
	v_exp_f32_e32 v157, v157
	v_exp_f32_e32 v158, v158
	v_exp_f32_e32 v159, v159
	v_pk_add_f32 v[140:141], v[140:141], v[156:157]
	v_pk_add_f32 v[140:141], v[140:141], v[158:159]
	v_cvt_pk_bf16_f32 v190, v156, v157
	v_cvt_pk_bf16_f32 v191, v158, v159
	s_add_i32 s77, s40, 0
	s_cmp_lt_u32 s77, s44
	s_cselect_b32 s76, s70, s71
	v_min_f32_e32 v152, s76, v236
	v_min_f32_e32 v153, s76, v237
	v_min_f32_e32 v154, s76, v238
	v_min_f32_e32 v155, s76, v239
	v_min_f32_e32 v156, s76, v244
	v_min_f32_e32 v157, s76, v245
	v_min_f32_e32 v158, s76, v246
	v_min_f32_e32 v159, s76, v247
	s_waitcnt lgkmcnt(0)
	v_mfma_f32_16x16x32_bf16 v[236:239], v[220:223], v[48:51], 0
	v_mfma_f32_16x16x32_bf16 v[236:239], v[224:227], v[52:55], v[236:239]
	v_mfma_f32_16x16x32_bf16 v[244:247], v[220:223], v[56:59], 0
	v_mfma_f32_16x16x32_bf16 v[244:247], v[224:227], v[60:63], v[244:247]
	s_waitcnt vmcnt(10)
	ds_write_b128 v165, v[0:3]
	ds_write_b128 v165, v[4:7] offset:1152
	ds_read_b128 v[228:231], v175 offset:2304
	ds_read_b128 v[232:235], v175 offset:2368
	v_pk_mul_f32 v[152:153], v[152:153], s[72:73]
	v_pk_mul_f32 v[154:155], v[154:155], s[72:73]
	v_exp_f32_e32 v152, v152
	v_exp_f32_e32 v153, v153
	v_exp_f32_e32 v154, v154
	v_exp_f32_e32 v155, v155
	v_pk_add_f32 v[138:139], v[138:139], v[152:153]
	v_pk_add_f32 v[138:139], v[138:139], v[154:155]
	v_cvt_pk_bf16_f32 v120, v152, v153
	v_cvt_pk_bf16_f32 v121, v154, v155
	v_pk_mul_f32 v[156:157], v[156:157], s[72:73]
	v_pk_mul_f32 v[158:159], v[158:159], s[72:73]
	v_exp_f32_e32 v156, v156
	v_exp_f32_e32 v157, v157
	v_exp_f32_e32 v158, v158
	v_exp_f32_e32 v159, v159
	v_pk_add_f32 v[140:141], v[140:141], v[156:157]
	v_pk_add_f32 v[140:141], v[140:141], v[158:159]
	v_cvt_pk_bf16_f32 v192, v156, v157
	v_cvt_pk_bf16_f32 v193, v158, v159
	s_add_i32 s77, s40, 16
	s_cmp_lt_u32 s77, s44
	s_cselect_b32 s76, s70, s71
	v_min_f32_e32 v152, s76, v240
	v_min_f32_e32 v153, s76, v241
	v_min_f32_e32 v154, s76, v242
	v_min_f32_e32 v155, s76, v243
	v_min_f32_e32 v156, s76, v248
	v_min_f32_e32 v157, s76, v249
	v_min_f32_e32 v158, s76, v250
	v_min_f32_e32 v159, s76, v251
	s_waitcnt lgkmcnt(0)
	v_mfma_f32_16x16x32_bf16 v[240:243], v[228:231], v[48:51], 0
	v_mfma_f32_16x16x32_bf16 v[240:243], v[232:235], v[52:55], v[240:243]
	v_mfma_f32_16x16x32_bf16 v[248:251], v[228:231], v[56:59], 0
	v_mfma_f32_16x16x32_bf16 v[248:251], v[232:235], v[60:63], v[248:251]
	s_waitcnt vmcnt(8)
	ds_write_b128 v165, v[8:11] offset:2304
	ds_write_b128 v165, v[12:15] offset:3456
	ds_read_b128 v[204:207], v175
	ds_read_b128 v[208:211], v175 offset:64
	v_pk_mul_f32 v[152:153], v[152:153], s[72:73]
	v_pk_mul_f32 v[154:155], v[154:155], s[72:73]
	v_exp_f32_e32 v152, v152
	v_exp_f32_e32 v153, v153
	v_exp_f32_e32 v154, v154
	v_exp_f32_e32 v155, v155
	v_pk_add_f32 v[138:139], v[138:139], v[152:153]
	v_pk_add_f32 v[138:139], v[138:139], v[154:155]
	v_cvt_pk_bf16_f32 v122, v152, v153
	v_cvt_pk_bf16_f32 v123, v154, v155
	v_pk_mul_f32 v[156:157], v[156:157], s[72:73]
	v_pk_mul_f32 v[158:159], v[158:159], s[72:73]
	v_exp_f32_e32 v156, v156
	v_exp_f32_e32 v157, v157
	v_exp_f32_e32 v158, v158
	v_exp_f32_e32 v159, v159
	v_pk_add_f32 v[140:141], v[140:141], v[156:157]
	v_pk_add_f32 v[140:141], v[140:141], v[158:159]
	v_cvt_pk_bf16_f32 v194, v156, v157
	v_cvt_pk_bf16_f32 v195, v158, v159
	s_add_i32 s77, s40, 32
	s_cmp_lt_u32 s77, s44
	s_cselect_b32 s76, s70, s71
	v_min_f32_e32 v152, s76, v236
	v_min_f32_e32 v153, s76, v237
	v_min_f32_e32 v154, s76, v238
	v_min_f32_e32 v155, s76, v239
	v_min_f32_e32 v156, s76, v244
	v_min_f32_e32 v157, s76, v245
	v_min_f32_e32 v158, s76, v246
	v_min_f32_e32 v159, s76, v247
	s_waitcnt lgkmcnt(0)
	v_mfma_f32_16x16x32_bf16 v[236:239], v[204:207], v[48:51], 0
	v_mfma_f32_16x16x32_bf16 v[236:239], v[208:211], v[52:55], v[236:239]
	v_mfma_f32_16x16x32_bf16 v[244:247], v[204:207], v[56:59], 0
	v_mfma_f32_16x16x32_bf16 v[244:247], v[208:211], v[60:63], v[244:247]
	ds_read_b128 v[212:215], v175 offset:2304
	ds_read_b128 v[216:219], v175 offset:2368
	v_pk_mul_f32 v[152:153], v[152:153], s[72:73]
	v_pk_mul_f32 v[154:155], v[154:155], s[72:73]
	v_exp_f32_e32 v152, v152
	v_exp_f32_e32 v153, v153
	v_exp_f32_e32 v154, v154
	v_exp_f32_e32 v155, v155
	v_pk_add_f32 v[138:139], v[138:139], v[152:153]
	v_pk_add_f32 v[138:139], v[138:139], v[154:155]
	v_cvt_pk_bf16_f32 v124, v152, v153
	v_cvt_pk_bf16_f32 v125, v154, v155
	v_pk_mul_f32 v[156:157], v[156:157], s[72:73]
	v_pk_mul_f32 v[158:159], v[158:159], s[72:73]
	v_exp_f32_e32 v156, v156
	v_exp_f32_e32 v157, v157
	v_exp_f32_e32 v158, v158
	v_exp_f32_e32 v159, v159
	v_pk_add_f32 v[140:141], v[140:141], v[156:157]
	v_pk_add_f32 v[140:141], v[140:141], v[158:159]
	v_cvt_pk_bf16_f32 v196, v156, v157
	v_cvt_pk_bf16_f32 v197, v158, v159
	s_add_i32 s77, s40, 48
	s_cmp_lt_u32 s77, s44
	s_cselect_b32 s76, s70, s71
	v_min_f32_e32 v152, s76, v240
	v_min_f32_e32 v153, s76, v241
	v_min_f32_e32 v154, s76, v242
	v_min_f32_e32 v155, s76, v243
	v_min_f32_e32 v156, s76, v248
	v_min_f32_e32 v157, s76, v249
	v_min_f32_e32 v158, s76, v250
	v_min_f32_e32 v159, s76, v251
	s_waitcnt lgkmcnt(0)
	v_mfma_f32_16x16x32_bf16 v[248:251], v[212:215], v[56:59], 0
	v_mfma_f32_16x16x32_bf16 v[248:251], v[216:219], v[60:63], v[248:251]
	v_pk_mul_f32 v[152:153], v[152:153], s[72:73]
	v_pk_mul_f32 v[154:155], v[154:155], s[72:73]
	v_exp_f32_e32 v152, v152
	v_exp_f32_e32 v153, v153
	v_exp_f32_e32 v154, v154
	v_exp_f32_e32 v155, v155
	v_pk_add_f32 v[138:139], v[138:139], v[152:153]
	v_pk_add_f32 v[138:139], v[138:139], v[154:155]
	v_cvt_pk_bf16_f32 v126, v152, v153
	v_cvt_pk_bf16_f32 v127, v154, v155
	v_pk_mul_f32 v[156:157], v[156:157], s[72:73]
	v_pk_mul_f32 v[158:159], v[158:159], s[72:73]
	v_exp_f32_e32 v156, v156
	v_exp_f32_e32 v157, v157
	v_exp_f32_e32 v158, v158
	v_exp_f32_e32 v159, v159
	v_pk_add_f32 v[140:141], v[140:141], v[156:157]
	v_pk_add_f32 v[140:141], v[140:141], v[158:159]
	v_cvt_pk_bf16_f32 v198, v156, v157
	v_cvt_pk_bf16_f32 v199, v158, v159
	s_add_i32 s77, s40, 64
	s_cmp_lt_u32 s77, s44
	s_cselect_b32 s76, s70, s71
	v_min_f32_e32 v152, s76, v236
	v_min_f32_e32 v153, s76, v237
	v_min_f32_e32 v154, s76, v238
	v_min_f32_e32 v155, s76, v239
	v_min_f32_e32 v156, s76, v244
	v_min_f32_e32 v157, s76, v245
	v_min_f32_e32 v158, s76, v246
	v_min_f32_e32 v159, s76, v247
	v_pk_mul_f32 v[152:153], v[152:153], s[72:73]
	v_pk_mul_f32 v[154:155], v[154:155], s[72:73]
	v_exp_f32_e32 v152, v152
	v_exp_f32_e32 v153, v153
	v_exp_f32_e32 v154, v154
	v_exp_f32_e32 v155, v155
	v_cndmask_b32_e64 v152, 0, v152, s[62:63]
	v_cndmask_b32_e64 v153, 0, v153, s[64:65]
	v_cndmask_b32_e64 v154, 0, v154, s[66:67]
	v_cndmask_b32_e64 v155, 0, v155, s[68:69]
	v_pk_add_f32 v[138:139], v[138:139], v[152:153]
	v_pk_add_f32 v[138:139], v[138:139], v[154:155]
	v_cvt_pk_bf16_f32 v128, v152, v153
	v_cvt_pk_bf16_f32 v129, v154, v155
	v_pk_mul_f32 v[156:157], v[156:157], s[72:73]
	v_pk_mul_f32 v[158:159], v[158:159], s[72:73]
	v_exp_f32_e32 v156, v156
	v_exp_f32_e32 v157, v157
	v_exp_f32_e32 v158, v158
	v_exp_f32_e32 v159, v159
	v_pk_add_f32 v[140:141], v[140:141], v[156:157]
	v_pk_add_f32 v[140:141], v[140:141], v[158:159]
	v_cvt_pk_bf16_f32 v200, v156, v157
	v_cvt_pk_bf16_f32 v201, v158, v159
	s_add_i32 s77, s40, 80
	s_cmp_lt_u32 s77, s44
	s_cselect_b32 s76, s70, s71
	v_min_f32_e32 v156, s76, v248
	v_min_f32_e32 v157, s76, v249
	v_min_f32_e32 v158, s76, v250
	v_min_f32_e32 v159, s76, v251
	v_pk_mul_f32 v[156:157], v[156:157], s[72:73]
	v_pk_mul_f32 v[158:159], v[158:159], s[72:73]
	v_exp_f32_e32 v156, v156
	v_exp_f32_e32 v157, v157
	v_exp_f32_e32 v158, v158
	v_exp_f32_e32 v159, v159
	v_cndmask_b32_e64 v156, 0, v156, s[62:63]
	v_cndmask_b32_e64 v157, 0, v157, s[64:65]
	v_cndmask_b32_e64 v158, 0, v158, s[66:67]
	v_cndmask_b32_e64 v159, 0, v159, s[68:69]
	v_pk_add_f32 v[140:141], v[140:141], v[156:157]
	v_pk_add_f32 v[140:141], v[140:141], v[158:159]
	v_cvt_pk_bf16_f32 v202, v156, v157
	v_cvt_pk_bf16_f32 v203, v158, v159
	v_add_f32_e32 v132, v138, v139
	v_add_f32_e32 v133, v140, v141
	v_add_u32_e32 v134, s42, v160
	v_lshlrev_b32_e32 v134, 4, v134
	v_add_u32_e32 v134, s43, v134
	v_subrev_u32_e32 v135, s15, v134
	v_lshrrev_b32_e32 v136, 4, v135
	v_add_u32_e32 v136, v136, v135
	v_mad_u32_u24 v176, v136, s79, v161
	v_lshl_add_u32 v177, v135, 2, s80
	s_and_b32 s2, s43, 3
	s_lshl_b32 s2, s2, s13
	s_lshr_b32 s3, s43, 2
	s_add_i32 s2, s2, s3
	s_lshl_b32 s2, s2, 7
	s_add_u32 s86, s20, s2
	s_addc_u32 s87, s21, 0
	s_add_i32 s2, s42, -64
	v_add_u32_e32 v136, s2, v164
	v_med3_i32 v136, v136, 0, s14
	v_lshl_add_u32 v136, v136, 9, v162
	global_load_dwordx4 v[0:3], v136, s[86:87]
	s_add_i32 s2, s42, -56
	v_add_u32_e32 v135, s2, v164
	v_med3_i32 v135, v135, 0, s14
	v_lshl_add_u32 v135, v135, 9, v162
	global_load_dwordx4 v[4:7], v135, s[86:87]
	s_add_i32 s2, s42, -48
	v_add_u32_e32 v136, s2, v164
	v_med3_i32 v136, v136, 0, s14
	v_lshl_add_u32 v136, v136, 9, v162
	global_load_dwordx4 v[8:11], v136, s[86:87]
	s_add_i32 s2, s42, -40
	v_add_u32_e32 v135, s2, v164
	v_med3_i32 v135, v135, 0, s14
	v_lshl_add_u32 v135, v135, 9, v162
	global_load_dwordx4 v[12:15], v135, s[86:87]
	ds_bpermute_b32 v142, v167, v132
	s_waitcnt lgkmcnt(0)
	v_add_f32_e32 v132, v132, v142
	ds_bpermute_b32 v142, v168, v132
	s_waitcnt lgkmcnt(0)
	v_add_f32_e32 v132, v132, v142
	ds_bpermute_b32 v142, v167, v133
	s_waitcnt lgkmcnt(0)
	v_add_f32_e32 v133, v133, v142
	ds_bpermute_b32 v142, v168, v133
	s_waitcnt lgkmcnt(0)
	v_add_f32_e32 v133, v133, v142
	ds_write_b128 v165, v[64:67]
	ds_write_b128 v165, v[68:71] offset:1152
	ds_write_b128 v165, v[72:75] offset:2304
	ds_write_b128 v165, v[76:79] offset:3456
	s_waitcnt lgkmcnt(0)
	ds_read_b64_tr_b16 v[236:237], v166
	ds_read_b64_tr_b16 v[238:239], v166 offset:2304
	ds_read_b64_tr_b16 v[240:241], v166 offset:32
	ds_read_b64_tr_b16 v[242:243], v166 offset:2336
	ds_read_b64_tr_b16 v[244:245], v166 offset:64
	ds_read_b64_tr_b16 v[246:247], v166 offset:2368
	ds_read_b64_tr_b16 v[248:249], v166 offset:96
	ds_read_b64_tr_b16 v[250:251], v166 offset:2400
	s_waitcnt lgkmcnt(0)
	ds_write_b128 v165, v[80:83]
	ds_write_b128 v165, v[84:87] offset:1152
	ds_write_b128 v165, v[88:91] offset:2304
	ds_write_b128 v165, v[92:95] offset:3456
	v_mfma_f32_16x16x32_bf16 v[204:207], v[236:239], v[112:115], 0
	v_mfma_f32_16x16x32_bf16 v[208:211], v[240:243], v[112:115], 0
	v_mfma_f32_16x16x32_bf16 v[212:215], v[244:247], v[112:115], 0
	v_mfma_f32_16x16x32_bf16 v[216:219], v[248:251], v[112:115], 0
	v_mfma_f32_16x16x32_bf16 v[220:223], v[236:239], v[184:187], 0
	v_mfma_f32_16x16x32_bf16 v[224:227], v[240:243], v[184:187], 0
	v_mfma_f32_16x16x32_bf16 v[228:231], v[244:247], v[184:187], 0
	v_mfma_f32_16x16x32_bf16 v[232:235], v[248:251], v[184:187], 0
	s_waitcnt lgkmcnt(0)
	ds_read_b64_tr_b16 v[236:237], v166
	ds_read_b64_tr_b16 v[238:239], v166 offset:2304
	ds_read_b64_tr_b16 v[240:241], v166 offset:32
	ds_read_b64_tr_b16 v[242:243], v166 offset:2336
	ds_read_b64_tr_b16 v[244:245], v166 offset:64
	ds_read_b64_tr_b16 v[246:247], v166 offset:2368
	ds_read_b64_tr_b16 v[248:249], v166 offset:96
	ds_read_b64_tr_b16 v[250:251], v166 offset:2400
	s_waitcnt lgkmcnt(0)
	ds_write_b128 v165, v[96:99]
	ds_write_b128 v165, v[100:103] offset:1152
	ds_write_b128 v165, v[104:107] offset:2304
	ds_write_b128 v165, v[108:111] offset:3456
	v_mfma_f32_16x16x32_bf16 v[204:207], v[236:239], v[116:119], v[204:207]
	v_mfma_f32_16x16x32_bf16 v[208:211], v[240:243], v[116:119], v[208:211]
	v_mfma_f32_16x16x32_bf16 v[212:215], v[244:247], v[116:119], v[212:215]
	v_mfma_f32_16x16x32_bf16 v[216:219], v[248:251], v[116:119], v[216:219]
	v_mfma_f32_16x16x32_bf16 v[220:223], v[236:239], v[188:191], v[220:223]
	v_mfma_f32_16x16x32_bf16 v[224:227], v[240:243], v[188:191], v[224:227]
	v_mfma_f32_16x16x32_bf16 v[228:231], v[244:247], v[188:191], v[228:231]
	v_mfma_f32_16x16x32_bf16 v[232:235], v[248:251], v[188:191], v[232:235]
	s_waitcnt lgkmcnt(0)
	ds_read_b64_tr_b16 v[236:237], v166
	ds_read_b64_tr_b16 v[238:239], v166 offset:2304
	ds_read_b64_tr_b16 v[240:241], v166 offset:32
	ds_read_b64_tr_b16 v[242:243], v166 offset:2336
	ds_read_b64_tr_b16 v[244:245], v166 offset:64
	ds_read_b64_tr_b16 v[246:247], v166 offset:2368
	ds_read_b64_tr_b16 v[248:249], v166 offset:96
	ds_read_b64_tr_b16 v[250:251], v166 offset:2400
	s_waitcnt lgkmcnt(0)
	s_waitcnt vmcnt(8)
	ds_write_b128 v165, v[16:19]
	ds_write_b128 v165, v[20:23] offset:1152
	ds_write_b128 v165, v[24:27] offset:2304
	ds_write_b128 v165, v[28:31] offset:3456
	v_mfma_f32_16x16x32_bf16 v[204:207], v[236:239], v[120:123], v[204:207]
	v_mfma_f32_16x16x32_bf16 v[208:211], v[240:243], v[120:123], v[208:211]
	v_mfma_f32_16x16x32_bf16 v[212:215], v[244:247], v[120:123], v[212:215]
	v_mfma_f32_16x16x32_bf16 v[216:219], v[248:251], v[120:123], v[216:219]
	v_mfma_f32_16x16x32_bf16 v[220:223], v[236:239], v[192:195], v[220:223]
	v_mfma_f32_16x16x32_bf16 v[224:227], v[240:243], v[192:195], v[224:227]
	v_mfma_f32_16x16x32_bf16 v[228:231], v[244:247], v[192:195], v[228:231]
	v_mfma_f32_16x16x32_bf16 v[232:235], v[248:251], v[192:195], v[232:235]
	s_waitcnt lgkmcnt(0)
	ds_read_b64_tr_b16 v[236:237], v166
	ds_read_b64_tr_b16 v[238:239], v166 offset:2304
	ds_read_b64_tr_b16 v[240:241], v166 offset:32
	ds_read_b64_tr_b16 v[242:243], v166 offset:2336
	ds_read_b64_tr_b16 v[244:245], v166 offset:64
	ds_read_b64_tr_b16 v[246:247], v166 offset:2368
	ds_read_b64_tr_b16 v[248:249], v166 offset:96
	ds_read_b64_tr_b16 v[250:251], v166 offset:2400
	s_waitcnt lgkmcnt(0)
	s_add_i32 s2, s42, -32
	v_add_u32_e32 v136, s2, v164
	v_med3_i32 v136, v136, 0, s14
	v_lshl_add_u32 v136, v136, 9, v162
	global_load_dwordx4 v[16:19], v136, s[86:87]
	s_add_i32 s2, s42, -24
	v_add_u32_e32 v135, s2, v164
	v_med3_i32 v135, v135, 0, s14
	v_lshl_add_u32 v135, v135, 9, v162
	global_load_dwordx4 v[20:23], v135, s[86:87]
	s_add_i32 s2, s42, -16
	v_add_u32_e32 v136, s2, v164
	v_med3_i32 v136, v136, 0, s14
	v_lshl_add_u32 v136, v136, 9, v162
	global_load_dwordx4 v[24:27], v136, s[86:87]
	s_add_i32 s2, s42, -8
	v_add_u32_e32 v135, s2, v164
	v_med3_i32 v135, v135, 0, s14
	v_lshl_add_u32 v135, v135, 9, v162
	global_load_dwordx4 v[28:31], v135, s[86:87]
	s_waitcnt vmcnt(8)
	ds_write_b128 v165, v[32:35]
	ds_write_b128 v165, v[36:39] offset:1152
	ds_write_b128 v165, v[40:43] offset:2304
	ds_write_b128 v165, v[44:47] offset:3456
	v_mfma_f32_16x16x32_bf16 v[204:207], v[236:239], v[124:127], v[204:207]
	v_mfma_f32_16x16x32_bf16 v[208:211], v[240:243], v[124:127], v[208:211]
	v_mfma_f32_16x16x32_bf16 v[212:215], v[244:247], v[124:127], v[212:215]
	v_mfma_f32_16x16x32_bf16 v[216:219], v[248:251], v[124:127], v[216:219]
	v_mfma_f32_16x16x32_bf16 v[220:223], v[236:239], v[196:199], v[220:223]
	v_mfma_f32_16x16x32_bf16 v[224:227], v[240:243], v[196:199], v[224:227]
	v_mfma_f32_16x16x32_bf16 v[228:231], v[244:247], v[196:199], v[228:231]
	v_mfma_f32_16x16x32_bf16 v[232:235], v[248:251], v[196:199], v[232:235]
	s_waitcnt lgkmcnt(0)
	ds_read_b64_tr_b16 v[236:237], v166
	ds_read_b64_tr_b16 v[238:239], v166 offset:2304
	ds_read_b64_tr_b16 v[240:241], v166 offset:32
	ds_read_b64_tr_b16 v[242:243], v166 offset:2336
	ds_read_b64_tr_b16 v[244:245], v166 offset:64
	ds_read_b64_tr_b16 v[246:247], v166 offset:2368
	ds_read_b64_tr_b16 v[248:249], v166 offset:96
	ds_read_b64_tr_b16 v[250:251], v166 offset:2400
	s_waitcnt lgkmcnt(0)
	s_add_i32 s2, s42, 0
	v_add_u32_e32 v136, s2, v164
	v_med3_i32 v136, v136, 0, s14
	v_lshl_add_u32 v136, v136, 9, v162
	global_load_dwordx4 v[32:35], v136, s[86:87]
	s_add_i32 s2, s42, 8
	v_add_u32_e32 v135, s2, v164
	v_med3_i32 v135, v135, 0, s14
	v_lshl_add_u32 v135, v135, 9, v162
	global_load_dwordx4 v[36:39], v135, s[86:87]
	s_add_i32 s2, s42, 16
	v_add_u32_e32 v136, s2, v164
	v_med3_i32 v136, v136, 0, s14
	v_lshl_add_u32 v136, v136, 9, v162
	global_load_dwordx4 v[40:43], v136, s[86:87]
	s_add_i32 s2, s42, 24
	v_add_u32_e32 v135, s2, v164
	v_med3_i32 v135, v135, 0, s14
	v_lshl_add_u32 v135, v135, 9, v162
	global_load_dwordx4 v[44:47], v135, s[86:87]
	v_mfma_f32_16x16x32_bf16 v[204:207], v[236:239], v[128:131], v[204:207]
	v_mfma_f32_16x16x32_bf16 v[208:211], v[240:243], v[128:131], v[208:211]
	v_mfma_f32_16x16x32_bf16 v[212:215], v[244:247], v[128:131], v[212:215]
	v_mfma_f32_16x16x32_bf16 v[216:219], v[248:251], v[128:131], v[216:219]
	v_mfma_f32_16x16x32_bf16 v[220:223], v[236:239], v[200:203], v[220:223]
	v_mfma_f32_16x16x32_bf16 v[224:227], v[240:243], v[200:203], v[224:227]
	v_mfma_f32_16x16x32_bf16 v[228:231], v[244:247], v[200:203], v[228:231]
	v_mfma_f32_16x16x32_bf16 v[232:235], v[248:251], v[200:203], v[232:235]
	s_add_i32 s2, s42, 32
	v_add_u32_e32 v136, s2, v164
	v_med3_i32 v136, v136, 0, s14
	v_lshl_add_u32 v136, v136, 9, v162
	global_load_dwordx4 v[120:123], v136, s[86:87]
	s_add_i32 s2, s42, 40
	v_add_u32_e32 v135, s2, v164
	v_med3_i32 v135, v135, 0, s14
	v_lshl_add_u32 v135, v135, 9, v162
	global_load_dwordx4 v[124:127], v135, s[86:87]
	s_add_i32 s2, s42, 48
	v_add_u32_e32 v136, s2, v164
	v_med3_i32 v136, v136, 0, s14
	v_lshl_add_u32 v136, v136, 9, v162
	global_load_dwordx4 v[192:195], v136, s[86:87]
	s_add_i32 s2, s42, 56
	v_add_u32_e32 v135, s2, v164
	v_med3_i32 v135, v135, 0, s14
	v_lshl_add_u32 v135, v135, 9, v162
	global_load_dwordx4 v[196:199], v135, s[86:87]
	s_and_b32 s2, s43, 3
	s_lshl_b32 s2, s2, s13
	s_lshr_b32 s3, s43, 2
	s_add_i32 s2, s2, s3
	s_lshl_b32 s2, s2, 7
	s_add_u32 s74, s22, s2
	s_addc_u32 s75, s23, 0
	s_add_i32 s2, s42, -64
	v_add_u32_e32 v137, s2, v164
	v_med3_i32 v137, v137, 0, s14
	v_lshl_add_u32 v137, v137, 9, v162
	global_load_dwordx4 v[64:67], v137, s[74:75]
	s_add_i32 s2, s42, -56
	v_add_u32_e32 v137, s2, v164
	v_med3_i32 v137, v137, 0, s14
	v_lshl_add_u32 v137, v137, 9, v162
	global_load_dwordx4 v[68:71], v137, s[74:75]
	s_add_i32 s2, s42, -48
	v_add_u32_e32 v137, s2, v164
	v_med3_i32 v137, v137, 0, s14
	v_lshl_add_u32 v137, v137, 9, v162
	global_load_dwordx4 v[72:75], v137, s[74:75]
	s_add_i32 s2, s42, -40
	v_add_u32_e32 v137, s2, v164
	v_med3_i32 v137, v137, 0, s14
	v_lshl_add_u32 v137, v137, 9, v162
	global_load_dwordx4 v[76:79], v137, s[74:75]
	s_and_b32 s2, s43, 3
	s_lshl_b32 s2, s2, s13
	s_lshr_b32 s3, s43, 2
	s_add_i32 s2, s2, s3
	s_lshl_b32 s2, s2, 7
	s_add_u32 s74, s22, s2
	s_addc_u32 s75, s23, 0
	s_add_i32 s2, s42, -32
	v_add_u32_e32 v137, s2, v164
	v_med3_i32 v137, v137, 0, s14
	v_lshl_add_u32 v137, v137, 9, v162
	global_load_dwordx4 v[80:83], v137, s[74:75]
	s_add_i32 s2, s42, -24
	v_add_u32_e32 v137, s2, v164
	v_med3_i32 v137, v137, 0, s14
	v_lshl_add_u32 v137, v137, 9, v162
	global_load_dwordx4 v[84:87], v137, s[74:75]
	s_add_i32 s2, s42, -16
	v_add_u32_e32 v137, s2, v164
	v_med3_i32 v137, v137, 0, s14
	v_lshl_add_u32 v137, v137, 9, v162
	global_load_dwordx4 v[88:91], v137, s[74:75]
	s_add_i32 s2, s42, -8
	v_add_u32_e32 v137, s2, v164
	v_med3_i32 v137, v137, 0, s14
	v_lshl_add_u32 v137, v137, 9, v162
	global_load_dwordx4 v[92:95], v137, s[74:75]
	s_and_b32 s2, s43, 3
	s_lshl_b32 s2, s2, s13
	s_lshr_b32 s3, s43, 2
	s_add_i32 s2, s2, s3
	s_lshl_b32 s2, s2, 7
	s_add_u32 s74, s22, s2
	s_addc_u32 s75, s23, 0
	s_add_i32 s2, s42, 0
	v_add_u32_e32 v137, s2, v164
	v_med3_i32 v137, v137, 0, s14
	v_lshl_add_u32 v137, v137, 9, v162
	global_load_dwordx4 v[96:99], v137, s[74:75]
	s_add_i32 s2, s42, 8
	v_add_u32_e32 v137, s2, v164
	v_med3_i32 v137, v137, 0, s14
	v_lshl_add_u32 v137, v137, 9, v162
	global_load_dwordx4 v[100:103], v137, s[74:75]
	s_add_i32 s2, s42, 16
	v_add_u32_e32 v137, s2, v164
	v_med3_i32 v137, v137, 0, s14
	v_lshl_add_u32 v137, v137, 9, v162
	global_load_dwordx4 v[104:107], v137, s[74:75]
	s_add_i32 s2, s42, 24
	v_add_u32_e32 v137, s2, v164
	v_med3_i32 v137, v137, 0, s14
	v_lshl_add_u32 v137, v137, 9, v162
	global_load_dwordx4 v[108:111], v137, s[74:75]
	ds_read_b128 v[236:239], v173 offset:0
	ds_read_b128 v[240:243], v173 offset:64
	ds_read_b128 v[244:247], v173 offset:128
	ds_read_b128 v[248:251], v173 offset:192
	ds_read_b32 v142, v174 offset:0
	s_waitcnt lgkmcnt(0)
	v_add_f32_e32 v204, v236, v204
	v_add_f32_e32 v205, v237, v205
	v_add_f32_e32 v206, v238, v206
	v_add_f32_e32 v207, v239, v207
	v_add_f32_e32 v208, v240, v208
	v_add_f32_e32 v209, v241, v209
	v_add_f32_e32 v210, v242, v210
	v_add_f32_e32 v211, v243, v211
	v_add_f32_e32 v212, v244, v212
	v_add_f32_e32 v213, v245, v213
	v_add_f32_e32 v214, v246, v214
	v_add_f32_e32 v215, v247, v215
	v_add_f32_e32 v216, v248, v216
	v_add_f32_e32 v217, v249, v217
	v_add_f32_e32 v218, v250, v218
	v_add_f32_e32 v219, v251, v219
	v_add_f32_e32 v132, v142, v132
	ds_write_b128 v173, v[204:207] offset:0
	ds_write_b128 v173, v[208:211] offset:64
	ds_write_b128 v173, v[212:215] offset:128
	ds_write_b128 v173, v[216:219] offset:192
	ds_write_b32 v174, v132 offset:0
	ds_read_b128 v[236:239], v173 offset:18496
	ds_read_b128 v[240:243], v173 offset:18560
	ds_read_b128 v[244:247], v173 offset:18624
	ds_read_b128 v[248:251], v173 offset:18688
	ds_read_b32 v142, v174 offset:256
	s_waitcnt lgkmcnt(0)
	v_add_f32_e32 v220, v236, v220
	v_add_f32_e32 v221, v237, v221
	v_add_f32_e32 v222, v238, v222
	v_add_f32_e32 v223, v239, v223
	v_add_f32_e32 v224, v240, v224
	v_add_f32_e32 v225, v241, v225
	v_add_f32_e32 v226, v242, v226
	v_add_f32_e32 v227, v243, v227
	v_add_f32_e32 v228, v244, v228
	v_add_f32_e32 v229, v245, v229
	v_add_f32_e32 v230, v246, v230
	v_add_f32_e32 v231, v247, v231
	v_add_f32_e32 v232, v248, v232
	v_add_f32_e32 v233, v249, v233
	v_add_f32_e32 v234, v250, v234
	v_add_f32_e32 v235, v251, v235
	v_add_f32_e32 v133, v142, v133
	ds_write_b128 v173, v[220:223] offset:18496
	ds_write_b128 v173, v[224:227] offset:18560
	ds_write_b128 v173, v[228:231] offset:18624
	ds_write_b128 v173, v[232:235] offset:18688
	ds_write_b32 v174, v133 offset:256
	s_waitcnt lgkmcnt(0)
	s_barrier
	s_mov_b32 s40, s42
	s_mov_b32 s41, s43
	v_mov_b32_e32 v173, v176
	v_mov_b32_e32 v174, v177
	s_lshr_b32 s44, s33, 4
	s_lshr_b32 s42, s15, 4
	s_add_i32 s43, s0, 8
	v_subrev_u32_e32 v143, s80, v174
	v_lshl_add_u32 v143, v143, 5, v161
	v_add_u32_e32 v143, 0x1b500, v143
	ds_read_b128 v[48:51], v143
	ds_read_b128 v[52:55], v143 offset:64
	s_waitcnt lgkmcnt(0)
	v_mov_b32_e32 v138, 0
	v_mov_b32_e32 v139, 0
	s_waitcnt vmcnt(24)
	ds_write_b128 v165, v[0:3]
	ds_write_b128 v165, v[4:7] offset:1152
	ds_write_b128 v165, v[8:11] offset:2304
	ds_write_b128 v165, v[12:15] offset:3456
	s_waitcnt lgkmcnt(0)
	ds_read_b128 v[204:207], v175
	ds_read_b128 v[208:211], v175 offset:64
	ds_read_b128 v[212:215], v175 offset:2304
	ds_read_b128 v[216:219], v175 offset:2368
	s_and_b32 s2, s41, 3
	s_lshl_b32 s2, s2, s39
	s_lshr_b32 s3, s41, 2
	s_add_i32 s2, s2, s3
	s_lshl_b32 s2, s2, 7
	s_add_u32 s86, s24, s2
	s_addc_u32 s87, s25, 0
	s_add_i32 s2, s40, 64
	v_add_u32_e32 v136, s2, v164
	v_med3_i32 v136, v136, 0, s38
	v_lshl_add_u32 v136, v136, 9, v162
	global_load_dwordx4 v[0:3], v136, s[86:87]
	s_add_i32 s2, s40, 72
	v_add_u32_e32 v135, s2, v164
	v_med3_i32 v135, v135, 0, s38
	v_lshl_add_u32 v135, v135, 9, v162
	global_load_dwordx4 v[4:7], v135, s[86:87]
	s_waitcnt vmcnt(22)
	s_waitcnt lgkmcnt(0)
	ds_write_b128 v165, v[16:19]
	ds_write_b128 v165, v[20:23] offset:1152
	ds_write_b128 v165, v[24:27] offset:2304
	ds_write_b128 v165, v[28:31] offset:3456
	v_mfma_f32_16x16x32_bf16 v[236:239], v[204:207], v[48:51], 0
	v_mfma_f32_16x16x32_bf16 v[236:239], v[208:211], v[52:55], v[236:239]
	v_mfma_f32_16x16x32_bf16 v[240:243], v[212:215], v[48:51], 0
	v_mfma_f32_16x16x32_bf16 v[240:243], v[216:219], v[52:55], v[240:243]
	s_waitcnt lgkmcnt(0)
	ds_read_b128 v[220:223], v175
	ds_read_b128 v[224:227], v175 offset:64
	s_and_b32 s2, s41, 3
	s_lshl_b32 s2, s2, s39
	s_lshr_b32 s3, s41, 2
	s_add_i32 s2, s2, s3
	s_lshl_b32 s2, s2, 7
	s_add_u32 s74, s26, s2
	s_addc_u32 s75, s27, 0
	s_add_i32 s2, s40, 32
	v_add_u32_e32 v137, s2, v164
	v_med3_i32 v137, v137, 0, s38
	v_lshl_add_u32 v137, v137, 9, v162
	global_load_dwordx4 v[16:19], v137, s[74:75]
	s_add_i32 s2, s40, 40
	v_add_u32_e32 v137, s2, v164
	v_med3_i32 v137, v137, 0, s38
	v_lshl_add_u32 v137, v137, 9, v162
	global_load_dwordx4 v[20:23], v137, s[74:75]
	s_add_i32 s2, s40, 48
	v_add_u32_e32 v137, s2, v164
	v_med3_i32 v137, v137, 0, s38
	v_lshl_add_u32 v137, v137, 9, v162
	global_load_dwordx4 v[24:27], v137, s[74:75]
	s_add_i32 s2, s40, 56
	v_add_u32_e32 v137, s2, v164
	v_med3_i32 v137, v137, 0, s38
	v_lshl_add_u32 v137, v137, 9, v162
	global_load_dwordx4 v[28:31], v137, s[74:75]
	s_nop 7
	s_add_i32 s77, s40, -64
	s_cmp_lt_u32 s77, s44
	s_cselect_b32 s76, s70, s71
	v_min_f32_e32 v152, s76, v236
	v_min_f32_e32 v153, s76, v237
	v_min_f32_e32 v154, s76, v238
	v_min_f32_e32 v155, s76, v239
	s_waitcnt lgkmcnt(0)
	v_mfma_f32_16x16x32_bf16 v[236:239], v[220:223], v[48:51], 0
	v_mfma_f32_16x16x32_bf16 v[236:239], v[224:227], v[52:55], v[236:239]
	s_waitcnt vmcnt(24)
	ds_write_b128 v165, v[32:35]
	ds_write_b128 v165, v[36:39] offset:1152
	ds_read_b128 v[228:231], v175 offset:2304
	ds_read_b128 v[232:235], v175 offset:2368
	v_pk_mul_f32 v[152:153], v[152:153], s[72:73]
	v_pk_mul_f32 v[154:155], v[154:155], s[72:73]
	v_exp_f32_e32 v152, v152
	v_exp_f32_e32 v153, v153
	v_exp_f32_e32 v154, v154
	v_exp_f32_e32 v155, v155
	v_cndmask_b32_e64 v152, 0, v152, s[54:55]
	v_cndmask_b32_e64 v153, 0, v153, s[56:57]
	v_cndmask_b32_e64 v154, 0, v154, s[58:59]
	v_cndmask_b32_e64 v155, 0, v155, s[60:61]
	v_pk_add_f32 v[138:139], v[138:139], v[152:153]
	v_pk_add_f32 v[138:139], v[138:139], v[154:155]
	v_cvt_pk_bf16_f32 v112, v152, v153
	v_cvt_pk_bf16_f32 v113, v154, v155
	s_add_i32 s77, s40, -48
	s_cmp_lt_u32 s77, s44
	s_cselect_b32 s76, s70, s71
	v_min_f32_e32 v152, s76, v240
	v_min_f32_e32 v153, s76, v241
	v_min_f32_e32 v154, s76, v242
	v_min_f32_e32 v155, s76, v243
	s_waitcnt lgkmcnt(0)
	v_mfma_f32_16x16x32_bf16 v[240:243], v[228:231], v[48:51], 0
	v_mfma_f32_16x16x32_bf16 v[240:243], v[232:235], v[52:55], v[240:243]
	s_waitcnt vmcnt(22)
	ds_write_b128 v165, v[40:43] offset:2304
	ds_write_b128 v165, v[44:47] offset:3456
	ds_read_b128 v[204:207], v175
	ds_read_b128 v[208:211], v175 offset:64
	v_pk_mul_f32 v[152:153], v[152:153], s[72:73]
	v_pk_mul_f32 v[154:155], v[154:155], s[72:73]
	v_exp_f32_e32 v152, v152
	v_exp_f32_e32 v153, v153
	v_exp_f32_e32 v154, v154
	v_exp_f32_e32 v155, v155
	v_pk_add_f32 v[138:139], v[138:139], v[152:153]
	v_pk_add_f32 v[138:139], v[138:139], v[154:155]
	v_cvt_pk_bf16_f32 v114, v152, v153
	v_cvt_pk_bf16_f32 v115, v154, v155
	s_add_i32 s77, s40, -32
	s_cmp_lt_u32 s77, s44
	s_cselect_b32 s76, s70, s71
	v_min_f32_e32 v152, s76, v236
	v_min_f32_e32 v153, s76, v237
	v_min_f32_e32 v154, s76, v238
	v_min_f32_e32 v155, s76, v239
	s_waitcnt lgkmcnt(0)
	v_mfma_f32_16x16x32_bf16 v[236:239], v[204:207], v[48:51], 0
	v_mfma_f32_16x16x32_bf16 v[236:239], v[208:211], v[52:55], v[236:239]
	s_and_b32 s2, s41, 3
	s_lshl_b32 s2, s2, s39
	s_lshr_b32 s3, s41, 2
	s_add_i32 s2, s2, s3
	s_lshl_b32 s2, s2, 7
	s_add_u32 s74, s26, s2
	s_addc_u32 s75, s27, 0
	s_add_i32 s2, s40, 64
	v_add_u32_e32 v137, s2, v164
	v_med3_i32 v137, v137, 0, s38
	v_lshl_add_u32 v137, v137, 9, v162
	global_load_dwordx4 v[32:35], v137, s[74:75]
	s_add_i32 s2, s40, 72
	v_add_u32_e32 v137, s2, v164
	v_med3_i32 v137, v137, 0, s38
	v_lshl_add_u32 v137, v137, 9, v162
	global_load_dwordx4 v[36:39], v137, s[74:75]
	s_waitcnt vmcnt(22)
	ds_write_b128 v165, v[120:123]
	ds_write_b128 v165, v[124:127] offset:1152
	ds_read_b128 v[212:215], v175 offset:2304
	ds_read_b128 v[216:219], v175 offset:2368
	v_pk_mul_f32 v[152:153], v[152:153], s[72:73]
	v_pk_mul_f32 v[154:155], v[154:155], s[72:73]
	v_exp_f32_e32 v152, v152
	v_exp_f32_e32 v153, v153
	v_exp_f32_e32 v154, v154
	v_exp_f32_e32 v155, v155
	v_pk_add_f32 v[138:139], v[138:139], v[152:153]
	v_pk_add_f32 v[138:139], v[138:139], v[154:155]
	v_cvt_pk_bf16_f32 v116, v152, v153
	v_cvt_pk_bf16_f32 v117, v154, v155
	s_add_i32 s77, s40, -16
	s_cmp_lt_u32 s77, s44
	s_cselect_b32 s76, s70, s71
	v_min_f32_e32 v152, s76, v240
	v_min_f32_e32 v153, s76, v241
	v_min_f32_e32 v154, s76, v242
	v_min_f32_e32 v155, s76, v243
	s_waitcnt lgkmcnt(0)
	v_mfma_f32_16x16x32_bf16 v[240:243], v[212:215], v[48:51], 0
	v_mfma_f32_16x16x32_bf16 v[240:243], v[216:219], v[52:55], v[240:243]
	s_waitcnt vmcnt(20)
	ds_write_b128 v165, v[192:195] offset:2304
	ds_write_b128 v165, v[196:199] offset:3456
	ds_read_b128 v[220:223], v175
	ds_read_b128 v[224:227], v175 offset:64
	v_pk_mul_f32 v[152:153], v[152:153], s[72:73]
	v_pk_mul_f32 v[154:155], v[154:155], s[72:73]
	v_exp_f32_e32 v152, v152
	v_exp_f32_e32 v153, v153
	v_exp_f32_e32 v154, v154
	v_exp_f32_e32 v155, v155
	v_pk_add_f32 v[138:139], v[138:139], v[152:153]
	v_pk_add_f32 v[138:139], v[138:139], v[154:155]
	v_cvt_pk_bf16_f32 v118, v152, v153
	v_cvt_pk_bf16_f32 v119, v154, v155
	s_add_i32 s77, s40, 0
	s_cmp_lt_u32 s77, s44
	s_cselect_b32 s76, s70, s71
	v_min_f32_e32 v152, s76, v236
	v_min_f32_e32 v153, s76, v237
	v_min_f32_e32 v154, s76, v238
	v_min_f32_e32 v155, s76, v239
	s_waitcnt lgkmcnt(0)
	v_mfma_f32_16x16x32_bf16 v[236:239], v[220:223], v[48:51], 0
	v_mfma_f32_16x16x32_bf16 v[236:239], v[224:227], v[52:55], v[236:239]
	s_waitcnt vmcnt(6)
	ds_write_b128 v165, v[0:3]
	ds_write_b128 v165, v[4:7] offset:1152
	ds_read_b128 v[228:231], v175 offset:2304
	ds_read_b128 v[232:235], v175 offset:2368
	v_pk_mul_f32 v[152:153], v[152:153], s[72:73]
	v_pk_mul_f32 v[154:155], v[154:155], s[72:73]
	v_exp_f32_e32 v152, v152
	v_exp_f32_e32 v153, v153
	v_exp_f32_e32 v154, v154
	v_exp_f32_e32 v155, v155
	v_pk_add_f32 v[138:139], v[138:139], v[152:153]
	v_pk_add_f32 v[138:139], v[138:139], v[154:155]
	v_cvt_pk_bf16_f32 v120, v152, v153
	v_cvt_pk_bf16_f32 v121, v154, v155
	s_add_i32 s77, s40, 16
	s_cmp_lt_u32 s77, s44
	s_cselect_b32 s76, s70, s71
	v_min_f32_e32 v152, s76, v240
	v_min_f32_e32 v153, s76, v241
	v_min_f32_e32 v154, s76, v242
	v_min_f32_e32 v155, s76, v243
	s_waitcnt lgkmcnt(0)
	v_mfma_f32_16x16x32_bf16 v[240:243], v[228:231], v[48:51], 0
	v_mfma_f32_16x16x32_bf16 v[240:243], v[232:235], v[52:55], v[240:243]
	ds_read_b128 v[204:207], v175
	ds_read_b128 v[208:211], v175 offset:64
	v_pk_mul_f32 v[152:153], v[152:153], s[72:73]
	v_pk_mul_f32 v[154:155], v[154:155], s[72:73]
	v_exp_f32_e32 v152, v152
	v_exp_f32_e32 v153, v153
	v_exp_f32_e32 v154, v154
	v_exp_f32_e32 v155, v155
	v_pk_add_f32 v[138:139], v[138:139], v[152:153]
	v_pk_add_f32 v[138:139], v[138:139], v[154:155]
	v_cvt_pk_bf16_f32 v122, v152, v153
	v_cvt_pk_bf16_f32 v123, v154, v155
	s_add_i32 s77, s40, 32
	s_cmp_lt_u32 s77, s44
	s_cselect_b32 s76, s70, s71
	v_min_f32_e32 v152, s76, v236
	v_min_f32_e32 v153, s76, v237
	v_min_f32_e32 v154, s76, v238
	v_min_f32_e32 v155, s76, v239
	s_waitcnt lgkmcnt(0)
	v_mfma_f32_16x16x32_bf16 v[236:239], v[204:207], v[48:51], 0
	v_mfma_f32_16x16x32_bf16 v[236:239], v[208:211], v[52:55], v[236:239]
	v_pk_mul_f32 v[152:153], v[152:153], s[72:73]
	v_pk_mul_f32 v[154:155], v[154:155], s[72:73]
	v_exp_f32_e32 v152, v152
	v_exp_f32_e32 v153, v153
	v_exp_f32_e32 v154, v154
	v_exp_f32_e32 v155, v155
	v_pk_add_f32 v[138:139], v[138:139], v[152:153]
	v_pk_add_f32 v[138:139], v[138:139], v[154:155]
	v_cvt_pk_bf16_f32 v124, v152, v153
	v_cvt_pk_bf16_f32 v125, v154, v155
	s_add_i32 s77, s40, 48
	s_cmp_lt_u32 s77, s44
	s_cselect_b32 s76, s70, s71
	v_min_f32_e32 v152, s76, v240
	v_min_f32_e32 v153, s76, v241
	v_min_f32_e32 v154, s76, v242
	v_min_f32_e32 v155, s76, v243
	v_pk_mul_f32 v[152:153], v[152:153], s[72:73]
	v_pk_mul_f32 v[154:155], v[154:155], s[72:73]
	v_exp_f32_e32 v152, v152
	v_exp_f32_e32 v153, v153
	v_exp_f32_e32 v154, v154
	v_exp_f32_e32 v155, v155
	v_pk_add_f32 v[138:139], v[138:139], v[152:153]
	v_pk_add_f32 v[138:139], v[138:139], v[154:155]
	v_cvt_pk_bf16_f32 v126, v152, v153
	v_cvt_pk_bf16_f32 v127, v154, v155
	s_add_i32 s77, s40, 64
	s_cmp_lt_u32 s77, s44
	s_cselect_b32 s76, s70, s71
	v_min_f32_e32 v152, s76, v236
	v_min_f32_e32 v153, s76, v237
	v_min_f32_e32 v154, s76, v238
	v_min_f32_e32 v155, s76, v239
	v_pk_mul_f32 v[152:153], v[152:153], s[72:73]
	v_pk_mul_f32 v[154:155], v[154:155], s[72:73]
	v_exp_f32_e32 v152, v152
	v_exp_f32_e32 v153, v153
	v_exp_f32_e32 v154, v154
	v_exp_f32_e32 v155, v155
	v_cndmask_b32_e64 v152, 0, v152, s[62:63]
	v_cndmask_b32_e64 v153, 0, v153, s[64:65]
	v_cndmask_b32_e64 v154, 0, v154, s[66:67]
	v_cndmask_b32_e64 v155, 0, v155, s[68:69]
	v_pk_add_f32 v[138:139], v[138:139], v[152:153]
	v_pk_add_f32 v[138:139], v[138:139], v[154:155]
	v_cvt_pk_bf16_f32 v128, v152, v153
	v_cvt_pk_bf16_f32 v129, v154, v155
	v_add_f32_e32 v132, v138, v139
	v_add_u32_e32 v134, s42, v160
	v_lshlrev_b32_e32 v134, 4, v134
	v_add_u32_e32 v134, s43, v134
	v_subrev_u32_e32 v135, s15, v134
	v_lshrrev_b32_e32 v136, 4, v135
	v_add_u32_e32 v136, v136, v135
	v_mad_u32_u24 v176, v136, s79, v161
	v_lshl_add_u32 v177, v135, 2, s80
	s_and_b32 s2, s43, 3
	s_lshl_b32 s2, s2, s13
	s_lshr_b32 s3, s43, 2
	s_add_i32 s2, s2, s3
	s_lshl_b32 s2, s2, 7
	s_add_u32 s86, s20, s2
	s_addc_u32 s87, s21, 0
	s_add_i32 s2, s42, -64
	v_add_u32_e32 v136, s2, v164
	v_med3_i32 v136, v136, 0, s14
	v_lshl_add_u32 v136, v136, 9, v162
	global_load_dwordx4 v[0:3], v136, s[86:87]
	s_add_i32 s2, s42, -56
	v_add_u32_e32 v135, s2, v164
	v_med3_i32 v135, v135, 0, s14
	v_lshl_add_u32 v135, v135, 9, v162
	global_load_dwordx4 v[4:7], v135, s[86:87]
	s_add_i32 s2, s42, -48
	v_add_u32_e32 v136, s2, v164
	v_med3_i32 v136, v136, 0, s14
	v_lshl_add_u32 v136, v136, 9, v162
	global_load_dwordx4 v[8:11], v136, s[86:87]
	s_add_i32 s2, s42, -40
	v_add_u32_e32 v135, s2, v164
	v_med3_i32 v135, v135, 0, s14
	v_lshl_add_u32 v135, v135, 9, v162
	global_load_dwordx4 v[12:15], v135, s[86:87]
	ds_bpermute_b32 v142, v167, v132
	s_waitcnt lgkmcnt(0)
	v_add_f32_e32 v132, v132, v142
	ds_bpermute_b32 v142, v168, v132
	s_waitcnt lgkmcnt(0)
	v_add_f32_e32 v132, v132, v142
	ds_write_b128 v165, v[64:67]
	ds_write_b128 v165, v[68:71] offset:1152
	ds_write_b128 v165, v[72:75] offset:2304
	ds_write_b128 v165, v[76:79] offset:3456
	s_waitcnt lgkmcnt(0)
	ds_read_b64_tr_b16 v[236:237], v166
	ds_read_b64_tr_b16 v[238:239], v166 offset:2304
	ds_read_b64_tr_b16 v[240:241], v166 offset:32
	ds_read_b64_tr_b16 v[242:243], v166 offset:2336
	ds_read_b64_tr_b16 v[244:245], v166 offset:64
	ds_read_b64_tr_b16 v[246:247], v166 offset:2368
	ds_read_b64_tr_b16 v[248:249], v166 offset:96
	ds_read_b64_tr_b16 v[250:251], v166 offset:2400
	s_waitcnt lgkmcnt(0)
	ds_write_b128 v165, v[80:83]
	ds_write_b128 v165, v[84:87] offset:1152
	ds_write_b128 v165, v[88:91] offset:2304
	ds_write_b128 v165, v[92:95] offset:3456
	v_mfma_f32_16x16x32_bf16 v[204:207], v[236:239], v[112:115], 0
	v_mfma_f32_16x16x32_bf16 v[208:211], v[240:243], v[112:115], 0
	v_mfma_f32_16x16x32_bf16 v[212:215], v[244:247], v[112:115], 0
	v_mfma_f32_16x16x32_bf16 v[216:219], v[248:251], v[112:115], 0
	s_waitcnt lgkmcnt(0)
	ds_read_b64_tr_b16 v[236:237], v166
	ds_read_b64_tr_b16 v[238:239], v166 offset:2304
	ds_read_b64_tr_b16 v[240:241], v166 offset:32
	ds_read_b64_tr_b16 v[242:243], v166 offset:2336
	ds_read_b64_tr_b16 v[244:245], v166 offset:64
	ds_read_b64_tr_b16 v[246:247], v166 offset:2368
	ds_read_b64_tr_b16 v[248:249], v166 offset:96
	ds_read_b64_tr_b16 v[250:251], v166 offset:2400
	s_waitcnt lgkmcnt(0)
	ds_write_b128 v165, v[96:99]
	ds_write_b128 v165, v[100:103] offset:1152
	ds_write_b128 v165, v[104:107] offset:2304
	ds_write_b128 v165, v[108:111] offset:3456
	v_mfma_f32_16x16x32_bf16 v[204:207], v[236:239], v[116:119], v[204:207]
	v_mfma_f32_16x16x32_bf16 v[208:211], v[240:243], v[116:119], v[208:211]
	v_mfma_f32_16x16x32_bf16 v[212:215], v[244:247], v[116:119], v[212:215]
	v_mfma_f32_16x16x32_bf16 v[216:219], v[248:251], v[116:119], v[216:219]
	s_waitcnt lgkmcnt(0)
	ds_read_b64_tr_b16 v[236:237], v166
	ds_read_b64_tr_b16 v[238:239], v166 offset:2304
	ds_read_b64_tr_b16 v[240:241], v166 offset:32
	ds_read_b64_tr_b16 v[242:243], v166 offset:2336
	ds_read_b64_tr_b16 v[244:245], v166 offset:64
	ds_read_b64_tr_b16 v[246:247], v166 offset:2368
	ds_read_b64_tr_b16 v[248:249], v166 offset:96
	ds_read_b64_tr_b16 v[250:251], v166 offset:2400
	s_waitcnt lgkmcnt(0)
	s_waitcnt vmcnt(6)
	ds_write_b128 v165, v[16:19]
	ds_write_b128 v165, v[20:23] offset:1152
	ds_write_b128 v165, v[24:27] offset:2304
	ds_write_b128 v165, v[28:31] offset:3456
	v_mfma_f32_16x16x32_bf16 v[204:207], v[236:239], v[120:123], v[204:207]
	v_mfma_f32_16x16x32_bf16 v[208:211], v[240:243], v[120:123], v[208:211]
	v_mfma_f32_16x16x32_bf16 v[212:215], v[244:247], v[120:123], v[212:215]
	v_mfma_f32_16x16x32_bf16 v[216:219], v[248:251], v[120:123], v[216:219]
	s_waitcnt lgkmcnt(0)
	ds_read_b64_tr_b16 v[236:237], v166
	ds_read_b64_tr_b16 v[238:239], v166 offset:2304
	ds_read_b64_tr_b16 v[240:241], v166 offset:32
	ds_read_b64_tr_b16 v[242:243], v166 offset:2336
	ds_read_b64_tr_b16 v[244:245], v166 offset:64
	ds_read_b64_tr_b16 v[246:247], v166 offset:2368
	ds_read_b64_tr_b16 v[248:249], v166 offset:96
	ds_read_b64_tr_b16 v[250:251], v166 offset:2400
	s_waitcnt lgkmcnt(0)
	s_add_i32 s2, s42, -32
	v_add_u32_e32 v136, s2, v164
	v_med3_i32 v136, v136, 0, s14
	v_lshl_add_u32 v136, v136, 9, v162
	global_load_dwordx4 v[16:19], v136, s[86:87]
	s_add_i32 s2, s42, -24
	v_add_u32_e32 v135, s2, v164
	v_med3_i32 v135, v135, 0, s14
	v_lshl_add_u32 v135, v135, 9, v162
	global_load_dwordx4 v[20:23], v135, s[86:87]
	s_add_i32 s2, s42, -16
	v_add_u32_e32 v136, s2, v164
	v_med3_i32 v136, v136, 0, s14
	v_lshl_add_u32 v136, v136, 9, v162
	global_load_dwordx4 v[24:27], v136, s[86:87]
	s_add_i32 s2, s42, -8
	v_add_u32_e32 v135, s2, v164
	v_med3_i32 v135, v135, 0, s14
	v_lshl_add_u32 v135, v135, 9, v162
	global_load_dwordx4 v[28:31], v135, s[86:87]
	s_waitcnt vmcnt(8)
	ds_write_b128 v165, v[32:35]
	ds_write_b128 v165, v[36:39] offset:1152
	v_mfma_f32_16x16x32_bf16 v[204:207], v[236:239], v[124:127], v[204:207]
	v_mfma_f32_16x16x32_bf16 v[208:211], v[240:243], v[124:127], v[208:211]
	v_mfma_f32_16x16x32_bf16 v[212:215], v[244:247], v[124:127], v[212:215]
	v_mfma_f32_16x16x32_bf16 v[216:219], v[248:251], v[124:127], v[216:219]
	s_waitcnt lgkmcnt(0)
	ds_read_b64_tr_b16 v[236:237], v166
	ds_read_b64_tr_b16 v[238:239], v166 offset:2304
	ds_read_b64_tr_b16 v[240:241], v166 offset:32
	ds_read_b64_tr_b16 v[242:243], v166 offset:2336
	ds_read_b64_tr_b16 v[244:245], v166 offset:64
	ds_read_b64_tr_b16 v[246:247], v166 offset:2368
	ds_read_b64_tr_b16 v[248:249], v166 offset:96
	ds_read_b64_tr_b16 v[250:251], v166 offset:2400
	s_waitcnt lgkmcnt(0)
	s_add_i32 s2, s42, 0
	v_add_u32_e32 v136, s2, v164
	v_med3_i32 v136, v136, 0, s14
	v_lshl_add_u32 v136, v136, 9, v162
	global_load_dwordx4 v[32:35], v136, s[86:87]
	s_add_i32 s2, s42, 8
	v_add_u32_e32 v135, s2, v164
	v_med3_i32 v135, v135, 0, s14
	v_lshl_add_u32 v135, v135, 9, v162
	global_load_dwordx4 v[36:39], v135, s[86:87]
	s_add_i32 s2, s42, 16
	v_add_u32_e32 v136, s2, v164
	v_med3_i32 v136, v136, 0, s14
	v_lshl_add_u32 v136, v136, 9, v162
	global_load_dwordx4 v[40:43], v136, s[86:87]
	s_add_i32 s2, s42, 24
	v_add_u32_e32 v135, s2, v164
	v_med3_i32 v135, v135, 0, s14
	v_lshl_add_u32 v135, v135, 9, v162
	global_load_dwordx4 v[44:47], v135, s[86:87]
	v_mfma_f32_16x16x32_bf16 v[204:207], v[236:239], v[128:131], v[204:207]
	v_mfma_f32_16x16x32_bf16 v[208:211], v[240:243], v[128:131], v[208:211]
	v_mfma_f32_16x16x32_bf16 v[212:215], v[244:247], v[128:131], v[212:215]
	v_mfma_f32_16x16x32_bf16 v[216:219], v[248:251], v[128:131], v[216:219]
	s_add_i32 s2, s42, 32
	v_add_u32_e32 v136, s2, v164
	v_med3_i32 v136, v136, 0, s14
	v_lshl_add_u32 v136, v136, 9, v162
	global_load_dwordx4 v[120:123], v136, s[86:87]
	s_add_i32 s2, s42, 40
	v_add_u32_e32 v135, s2, v164
	v_med3_i32 v135, v135, 0, s14
	v_lshl_add_u32 v135, v135, 9, v162
	global_load_dwordx4 v[124:127], v135, s[86:87]
	s_add_i32 s2, s42, 48
	v_add_u32_e32 v136, s2, v164
	v_med3_i32 v136, v136, 0, s14
	v_lshl_add_u32 v136, v136, 9, v162
	global_load_dwordx4 v[192:195], v136, s[86:87]
	s_add_i32 s2, s42, 56
	v_add_u32_e32 v135, s2, v164
	v_med3_i32 v135, v135, 0, s14
	v_lshl_add_u32 v135, v135, 9, v162
	global_load_dwordx4 v[196:199], v135, s[86:87]
	s_and_b32 s2, s43, 3
	s_lshl_b32 s2, s2, s13
	s_lshr_b32 s3, s43, 2
	s_add_i32 s2, s2, s3
	s_lshl_b32 s2, s2, 7
	s_add_u32 s74, s22, s2
	s_addc_u32 s75, s23, 0
	s_add_i32 s2, s42, -64
	v_add_u32_e32 v137, s2, v164
	v_med3_i32 v137, v137, 0, s14
	v_lshl_add_u32 v137, v137, 9, v162
	global_load_dwordx4 v[64:67], v137, s[74:75]
	s_add_i32 s2, s42, -56
	v_add_u32_e32 v137, s2, v164
	v_med3_i32 v137, v137, 0, s14
	v_lshl_add_u32 v137, v137, 9, v162
	global_load_dwordx4 v[68:71], v137, s[74:75]
	s_add_i32 s2, s42, -48
	v_add_u32_e32 v137, s2, v164
	v_med3_i32 v137, v137, 0, s14
	v_lshl_add_u32 v137, v137, 9, v162
	global_load_dwordx4 v[72:75], v137, s[74:75]
	s_add_i32 s2, s42, -40
	v_add_u32_e32 v137, s2, v164
	v_med3_i32 v137, v137, 0, s14
	v_lshl_add_u32 v137, v137, 9, v162
	global_load_dwordx4 v[76:79], v137, s[74:75]
	s_and_b32 s2, s43, 3
	s_lshl_b32 s2, s2, s13
	s_lshr_b32 s3, s43, 2
	s_add_i32 s2, s2, s3
	s_lshl_b32 s2, s2, 7
	s_add_u32 s74, s22, s2
	s_addc_u32 s75, s23, 0
	s_add_i32 s2, s42, -32
	v_add_u32_e32 v137, s2, v164
	v_med3_i32 v137, v137, 0, s14
	v_lshl_add_u32 v137, v137, 9, v162
	global_load_dwordx4 v[80:83], v137, s[74:75]
	s_add_i32 s2, s42, -24
	v_add_u32_e32 v137, s2, v164
	v_med3_i32 v137, v137, 0, s14
	v_lshl_add_u32 v137, v137, 9, v162
	global_load_dwordx4 v[84:87], v137, s[74:75]
	s_add_i32 s2, s42, -16
	v_add_u32_e32 v137, s2, v164
	v_med3_i32 v137, v137, 0, s14
	v_lshl_add_u32 v137, v137, 9, v162
	global_load_dwordx4 v[88:91], v137, s[74:75]
	s_add_i32 s2, s42, -8
	v_add_u32_e32 v137, s2, v164
	v_med3_i32 v137, v137, 0, s14
	v_lshl_add_u32 v137, v137, 9, v162
	global_load_dwordx4 v[92:95], v137, s[74:75]
	s_and_b32 s2, s43, 3
	s_lshl_b32 s2, s2, s13
	s_lshr_b32 s3, s43, 2
	s_add_i32 s2, s2, s3
	s_lshl_b32 s2, s2, 7
	s_add_u32 s74, s22, s2
	s_addc_u32 s75, s23, 0
	s_add_i32 s2, s42, 0
	v_add_u32_e32 v137, s2, v164
	v_med3_i32 v137, v137, 0, s14
	v_lshl_add_u32 v137, v137, 9, v162
	global_load_dwordx4 v[96:99], v137, s[74:75]
	s_add_i32 s2, s42, 8
	v_add_u32_e32 v137, s2, v164
	v_med3_i32 v137, v137, 0, s14
	v_lshl_add_u32 v137, v137, 9, v162
	global_load_dwordx4 v[100:103], v137, s[74:75]
	s_add_i32 s2, s42, 16
	v_add_u32_e32 v137, s2, v164
	v_med3_i32 v137, v137, 0, s14
	v_lshl_add_u32 v137, v137, 9, v162
	global_load_dwordx4 v[104:107], v137, s[74:75]
	s_add_i32 s2, s42, 24
	v_add_u32_e32 v137, s2, v164
	v_med3_i32 v137, v137, 0, s14
	v_lshl_add_u32 v137, v137, 9, v162
	global_load_dwordx4 v[108:111], v137, s[74:75]
	ds_read_b128 v[236:239], v173 offset:0
	ds_read_b128 v[240:243], v173 offset:64
	ds_read_b128 v[244:247], v173 offset:128
	ds_read_b128 v[248:251], v173 offset:192
	ds_read_b32 v142, v174 offset:0
	s_waitcnt lgkmcnt(0)
	v_add_f32_e32 v204, v236, v204
	v_add_f32_e32 v205, v237, v205
	v_add_f32_e32 v206, v238, v206
	v_add_f32_e32 v207, v239, v207
	v_add_f32_e32 v208, v240, v208
	v_add_f32_e32 v209, v241, v209
	v_add_f32_e32 v210, v242, v210
	v_add_f32_e32 v211, v243, v211
	v_add_f32_e32 v212, v244, v212
	v_add_f32_e32 v213, v245, v213
	v_add_f32_e32 v214, v246, v214
	v_add_f32_e32 v215, v247, v215
	v_add_f32_e32 v216, v248, v216
	v_add_f32_e32 v217, v249, v217
	v_add_f32_e32 v218, v250, v218
	v_add_f32_e32 v219, v251, v219
	v_add_f32_e32 v132, v142, v132
	ds_write_b128 v173, v[204:207] offset:0
	ds_write_b128 v173, v[208:211] offset:64
	ds_write_b128 v173, v[212:215] offset:128
	ds_write_b128 v173, v[216:219] offset:192
	ds_write_b32 v174, v132 offset:0
	s_mov_b32 s40, s42
	s_mov_b32 s41, s43
	v_mov_b32_e32 v173, v176
	v_mov_b32_e32 v174, v177
	s_lshr_b32 s44, s33, 4
	s_add_i32 s45, s10, s8
	s_cmp_lt_u32 s45, 0x800
	s_cbranch_scc1 .Latt_newunit
	s_mov_b32 s37, 1
	s_branch .Latt_ud_done

.Latt_ud_done:
	s_lshl_b32 s2, s0, 5
	s_add_i32 s42, s15, s2
	s_mov_b32 s43, 0
	v_subrev_u32_e32 v143, s80, v174
	v_lshl_add_u32 v143, v143, 5, v161
	v_add_u32_e32 v143, 0x1b500, v143
	ds_read_b128 v[48:51], v143
	ds_read_b128 v[52:55], v143 offset:64
	s_waitcnt lgkmcnt(0)
	v_mov_b32_e32 v138, 0
	v_mov_b32_e32 v139, 0
	s_waitcnt vmcnt(24)
	ds_write_b128 v165, v[0:3]
	ds_write_b128 v165, v[4:7] offset:1152
	ds_write_b128 v165, v[8:11] offset:2304
	ds_write_b128 v165, v[12:15] offset:3456
	s_waitcnt lgkmcnt(0)
	ds_read_b128 v[204:207], v175
	ds_read_b128 v[208:211], v175 offset:64
	ds_read_b128 v[212:215], v175 offset:2304
	ds_read_b128 v[216:219], v175 offset:2368
	s_and_b32 s2, s41, 3
	s_lshl_b32 s2, s2, s39
	s_lshr_b32 s3, s41, 2
	s_add_i32 s2, s2, s3
	s_lshl_b32 s2, s2, 7
	s_add_u32 s86, s24, s2
	s_addc_u32 s87, s25, 0
	s_add_i32 s2, s40, 64
	v_add_u32_e32 v136, s2, v164
	v_med3_i32 v136, v136, 0, s38
	v_lshl_add_u32 v136, v136, 9, v162
	global_load_dwordx4 v[0:3], v136, s[86:87]
	s_add_i32 s2, s40, 72
	v_add_u32_e32 v135, s2, v164
	v_med3_i32 v135, v135, 0, s38
	v_lshl_add_u32 v135, v135, 9, v162
	global_load_dwordx4 v[4:7], v135, s[86:87]
	s_waitcnt vmcnt(22)
	s_waitcnt lgkmcnt(0)
	ds_write_b128 v165, v[16:19]
	ds_write_b128 v165, v[20:23] offset:1152
	ds_write_b128 v165, v[24:27] offset:2304
	ds_write_b128 v165, v[28:31] offset:3456
	v_mfma_f32_16x16x32_bf16 v[236:239], v[204:207], v[48:51], 0
	v_mfma_f32_16x16x32_bf16 v[236:239], v[208:211], v[52:55], v[236:239]
	v_mfma_f32_16x16x32_bf16 v[240:243], v[212:215], v[48:51], 0
	v_mfma_f32_16x16x32_bf16 v[240:243], v[216:219], v[52:55], v[240:243]
	s_waitcnt lgkmcnt(0)
	ds_read_b128 v[220:223], v175
	ds_read_b128 v[224:227], v175 offset:64
	s_and_b32 s2, s41, 3
	s_lshl_b32 s2, s2, s39
	s_lshr_b32 s3, s41, 2
	s_add_i32 s2, s2, s3
	s_lshl_b32 s2, s2, 7
	s_add_u32 s74, s26, s2
	s_addc_u32 s75, s27, 0
	s_add_i32 s2, s40, 32
	v_add_u32_e32 v137, s2, v164
	v_med3_i32 v137, v137, 0, s38
	v_lshl_add_u32 v137, v137, 9, v162
	global_load_dwordx4 v[16:19], v137, s[74:75]
	s_add_i32 s2, s40, 40
	v_add_u32_e32 v137, s2, v164
	v_med3_i32 v137, v137, 0, s38
	v_lshl_add_u32 v137, v137, 9, v162
	global_load_dwordx4 v[20:23], v137, s[74:75]
	s_add_i32 s2, s40, 48
	v_add_u32_e32 v137, s2, v164
	v_med3_i32 v137, v137, 0, s38
	v_lshl_add_u32 v137, v137, 9, v162
	global_load_dwordx4 v[24:27], v137, s[74:75]
	s_add_i32 s2, s40, 56
	v_add_u32_e32 v137, s2, v164
	v_med3_i32 v137, v137, 0, s38
	v_lshl_add_u32 v137, v137, 9, v162
	global_load_dwordx4 v[28:31], v137, s[74:75]
	s_nop 7
	s_add_i32 s77, s40, -64
	s_cmp_lt_u32 s77, s44
	s_cselect_b32 s76, s70, s71
	v_min_f32_e32 v152, s76, v236
	v_min_f32_e32 v153, s76, v237
	v_min_f32_e32 v154, s76, v238
	v_min_f32_e32 v155, s76, v239
	s_waitcnt lgkmcnt(0)
	v_mfma_f32_16x16x32_bf16 v[236:239], v[220:223], v[48:51], 0
	v_mfma_f32_16x16x32_bf16 v[236:239], v[224:227], v[52:55], v[236:239]
	s_waitcnt vmcnt(24)
	ds_write_b128 v165, v[32:35]
	ds_write_b128 v165, v[36:39] offset:1152
	ds_read_b128 v[228:231], v175 offset:2304
	ds_read_b128 v[232:235], v175 offset:2368
	v_pk_mul_f32 v[152:153], v[152:153], s[72:73]
	v_pk_mul_f32 v[154:155], v[154:155], s[72:73]
	v_exp_f32_e32 v152, v152
	v_exp_f32_e32 v153, v153
	v_exp_f32_e32 v154, v154
	v_exp_f32_e32 v155, v155
	v_cndmask_b32_e64 v152, 0, v152, s[54:55]
	v_cndmask_b32_e64 v153, 0, v153, s[56:57]
	v_cndmask_b32_e64 v154, 0, v154, s[58:59]
	v_cndmask_b32_e64 v155, 0, v155, s[60:61]
	v_pk_add_f32 v[138:139], v[138:139], v[152:153]
	v_pk_add_f32 v[138:139], v[138:139], v[154:155]
	v_cvt_pk_bf16_f32 v112, v152, v153
	v_cvt_pk_bf16_f32 v113, v154, v155
	s_add_i32 s77, s40, -48
	s_cmp_lt_u32 s77, s44
	s_cselect_b32 s76, s70, s71
	v_min_f32_e32 v152, s76, v240
	v_min_f32_e32 v153, s76, v241
	v_min_f32_e32 v154, s76, v242
	v_min_f32_e32 v155, s76, v243
	s_waitcnt lgkmcnt(0)
	v_mfma_f32_16x16x32_bf16 v[240:243], v[228:231], v[48:51], 0
	v_mfma_f32_16x16x32_bf16 v[240:243], v[232:235], v[52:55], v[240:243]
	s_waitcnt vmcnt(22)
	ds_write_b128 v165, v[40:43] offset:2304
	ds_write_b128 v165, v[44:47] offset:3456
	ds_read_b128 v[204:207], v175
	ds_read_b128 v[208:211], v175 offset:64
	v_pk_mul_f32 v[152:153], v[152:153], s[72:73]
	v_pk_mul_f32 v[154:155], v[154:155], s[72:73]
	v_exp_f32_e32 v152, v152
	v_exp_f32_e32 v153, v153
	v_exp_f32_e32 v154, v154
	v_exp_f32_e32 v155, v155
	v_pk_add_f32 v[138:139], v[138:139], v[152:153]
	v_pk_add_f32 v[138:139], v[138:139], v[154:155]
	v_cvt_pk_bf16_f32 v114, v152, v153
	v_cvt_pk_bf16_f32 v115, v154, v155
	s_add_i32 s77, s40, -32
	s_cmp_lt_u32 s77, s44
	s_cselect_b32 s76, s70, s71
	v_min_f32_e32 v152, s76, v236
	v_min_f32_e32 v153, s76, v237
	v_min_f32_e32 v154, s76, v238
	v_min_f32_e32 v155, s76, v239
	s_waitcnt lgkmcnt(0)
	v_mfma_f32_16x16x32_bf16 v[236:239], v[204:207], v[48:51], 0
	v_mfma_f32_16x16x32_bf16 v[236:239], v[208:211], v[52:55], v[236:239]
	s_and_b32 s2, s41, 3
	s_lshl_b32 s2, s2, s39
	s_lshr_b32 s3, s41, 2
	s_add_i32 s2, s2, s3
	s_lshl_b32 s2, s2, 7
	s_add_u32 s74, s26, s2
	s_addc_u32 s75, s27, 0
	s_add_i32 s2, s40, 64
	v_add_u32_e32 v137, s2, v164
	v_med3_i32 v137, v137, 0, s38
	v_lshl_add_u32 v137, v137, 9, v162
	global_load_dwordx4 v[32:35], v137, s[74:75]
	s_add_i32 s2, s40, 72
	v_add_u32_e32 v137, s2, v164
	v_med3_i32 v137, v137, 0, s38
	v_lshl_add_u32 v137, v137, 9, v162
	global_load_dwordx4 v[36:39], v137, s[74:75]
	s_waitcnt vmcnt(22)
	ds_write_b128 v165, v[120:123]
	ds_write_b128 v165, v[124:127] offset:1152
	ds_read_b128 v[212:215], v175 offset:2304
	ds_read_b128 v[216:219], v175 offset:2368
	v_pk_mul_f32 v[152:153], v[152:153], s[72:73]
	v_pk_mul_f32 v[154:155], v[154:155], s[72:73]
	v_exp_f32_e32 v152, v152
	v_exp_f32_e32 v153, v153
	v_exp_f32_e32 v154, v154
	v_exp_f32_e32 v155, v155
	v_pk_add_f32 v[138:139], v[138:139], v[152:153]
	v_pk_add_f32 v[138:139], v[138:139], v[154:155]
	v_cvt_pk_bf16_f32 v116, v152, v153
	v_cvt_pk_bf16_f32 v117, v154, v155
	s_add_i32 s77, s40, -16
	s_cmp_lt_u32 s77, s44
	s_cselect_b32 s76, s70, s71
	v_min_f32_e32 v152, s76, v240
	v_min_f32_e32 v153, s76, v241
	v_min_f32_e32 v154, s76, v242
	v_min_f32_e32 v155, s76, v243
	s_waitcnt lgkmcnt(0)
	v_mfma_f32_16x16x32_bf16 v[240:243], v[212:215], v[48:51], 0
	v_mfma_f32_16x16x32_bf16 v[240:243], v[216:219], v[52:55], v[240:243]
	s_waitcnt vmcnt(20)
	ds_write_b128 v165, v[192:195] offset:2304
	ds_write_b128 v165, v[196:199] offset:3456
	ds_read_b128 v[220:223], v175
	ds_read_b128 v[224:227], v175 offset:64
	v_pk_mul_f32 v[152:153], v[152:153], s[72:73]
	v_pk_mul_f32 v[154:155], v[154:155], s[72:73]
	v_exp_f32_e32 v152, v152
	v_exp_f32_e32 v153, v153
	v_exp_f32_e32 v154, v154
	v_exp_f32_e32 v155, v155
	v_pk_add_f32 v[138:139], v[138:139], v[152:153]
	v_pk_add_f32 v[138:139], v[138:139], v[154:155]
	v_cvt_pk_bf16_f32 v118, v152, v153
	v_cvt_pk_bf16_f32 v119, v154, v155
	s_add_i32 s77, s40, 0
	s_cmp_lt_u32 s77, s44
	s_cselect_b32 s76, s70, s71
	v_min_f32_e32 v152, s76, v236
	v_min_f32_e32 v153, s76, v237
	v_min_f32_e32 v154, s76, v238
	v_min_f32_e32 v155, s76, v239
	s_waitcnt lgkmcnt(0)
	v_mfma_f32_16x16x32_bf16 v[236:239], v[220:223], v[48:51], 0
	v_mfma_f32_16x16x32_bf16 v[236:239], v[224:227], v[52:55], v[236:239]
	s_waitcnt vmcnt(6)
	ds_write_b128 v165, v[0:3]
	ds_write_b128 v165, v[4:7] offset:1152
	ds_read_b128 v[228:231], v175 offset:2304
	ds_read_b128 v[232:235], v175 offset:2368
	v_pk_mul_f32 v[152:153], v[152:153], s[72:73]
	v_pk_mul_f32 v[154:155], v[154:155], s[72:73]
	v_exp_f32_e32 v152, v152
	v_exp_f32_e32 v153, v153
	v_exp_f32_e32 v154, v154
	v_exp_f32_e32 v155, v155
	v_pk_add_f32 v[138:139], v[138:139], v[152:153]
	v_pk_add_f32 v[138:139], v[138:139], v[154:155]
	v_cvt_pk_bf16_f32 v120, v152, v153
	v_cvt_pk_bf16_f32 v121, v154, v155
	s_add_i32 s77, s40, 16
	s_cmp_lt_u32 s77, s44
	s_cselect_b32 s76, s70, s71
	v_min_f32_e32 v152, s76, v240
	v_min_f32_e32 v153, s76, v241
	v_min_f32_e32 v154, s76, v242
	v_min_f32_e32 v155, s76, v243
	s_waitcnt lgkmcnt(0)
	v_mfma_f32_16x16x32_bf16 v[240:243], v[228:231], v[48:51], 0
	v_mfma_f32_16x16x32_bf16 v[240:243], v[232:235], v[52:55], v[240:243]
	ds_read_b128 v[204:207], v175
	ds_read_b128 v[208:211], v175 offset:64
	v_pk_mul_f32 v[152:153], v[152:153], s[72:73]
	v_pk_mul_f32 v[154:155], v[154:155], s[72:73]
	v_exp_f32_e32 v152, v152
	v_exp_f32_e32 v153, v153
	v_exp_f32_e32 v154, v154
	v_exp_f32_e32 v155, v155
	v_pk_add_f32 v[138:139], v[138:139], v[152:153]
	v_pk_add_f32 v[138:139], v[138:139], v[154:155]
	v_cvt_pk_bf16_f32 v122, v152, v153
	v_cvt_pk_bf16_f32 v123, v154, v155
	s_add_i32 s77, s40, 32
	s_cmp_lt_u32 s77, s44
	s_cselect_b32 s76, s70, s71
	v_min_f32_e32 v152, s76, v236
	v_min_f32_e32 v153, s76, v237
	v_min_f32_e32 v154, s76, v238
	v_min_f32_e32 v155, s76, v239
	s_waitcnt lgkmcnt(0)
	v_mfma_f32_16x16x32_bf16 v[236:239], v[204:207], v[48:51], 0
	v_mfma_f32_16x16x32_bf16 v[236:239], v[208:211], v[52:55], v[236:239]
	v_pk_mul_f32 v[152:153], v[152:153], s[72:73]
	v_pk_mul_f32 v[154:155], v[154:155], s[72:73]
	v_exp_f32_e32 v152, v152
	v_exp_f32_e32 v153, v153
	v_exp_f32_e32 v154, v154
	v_exp_f32_e32 v155, v155
	v_pk_add_f32 v[138:139], v[138:139], v[152:153]
	v_pk_add_f32 v[138:139], v[138:139], v[154:155]
	v_cvt_pk_bf16_f32 v124, v152, v153
	v_cvt_pk_bf16_f32 v125, v154, v155
	s_add_i32 s77, s40, 48
	s_cmp_lt_u32 s77, s44
	s_cselect_b32 s76, s70, s71
	v_min_f32_e32 v152, s76, v240
	v_min_f32_e32 v153, s76, v241
	v_min_f32_e32 v154, s76, v242
	v_min_f32_e32 v155, s76, v243
	v_pk_mul_f32 v[152:153], v[152:153], s[72:73]
	v_pk_mul_f32 v[154:155], v[154:155], s[72:73]
	v_exp_f32_e32 v152, v152
	v_exp_f32_e32 v153, v153
	v_exp_f32_e32 v154, v154
	v_exp_f32_e32 v155, v155
	v_pk_add_f32 v[138:139], v[138:139], v[152:153]
	v_pk_add_f32 v[138:139], v[138:139], v[154:155]
	v_cvt_pk_bf16_f32 v126, v152, v153
	v_cvt_pk_bf16_f32 v127, v154, v155
	s_add_i32 s77, s40, 64
	s_cmp_lt_u32 s77, s44
	s_cselect_b32 s76, s70, s71
	v_min_f32_e32 v152, s76, v236
	v_min_f32_e32 v153, s76, v237
	v_min_f32_e32 v154, s76, v238
	v_min_f32_e32 v155, s76, v239
	v_pk_mul_f32 v[152:153], v[152:153], s[72:73]
	v_pk_mul_f32 v[154:155], v[154:155], s[72:73]
	v_exp_f32_e32 v152, v152
	v_exp_f32_e32 v153, v153
	v_exp_f32_e32 v154, v154
	v_exp_f32_e32 v155, v155
	v_cndmask_b32_e64 v152, 0, v152, s[62:63]
	v_cndmask_b32_e64 v153, 0, v153, s[64:65]
	v_cndmask_b32_e64 v154, 0, v154, s[66:67]
	v_cndmask_b32_e64 v155, 0, v155, s[68:69]
	v_pk_add_f32 v[138:139], v[138:139], v[152:153]
	v_pk_add_f32 v[138:139], v[138:139], v[154:155]
	v_cvt_pk_bf16_f32 v128, v152, v153
	v_cvt_pk_bf16_f32 v129, v154, v155
	v_add_f32_e32 v132, v138, v139
	v_add_u32_e32 v134, s42, v160
	v_add_u32_e32 v134, s43, v134
	v_subrev_u32_e32 v135, s15, v134
	v_lshrrev_b32_e32 v136, 4, v135
	v_add_u32_e32 v136, v136, v135
	v_mad_u32_u24 v176, v136, s79, v161
	v_lshl_add_u32 v177, v135, 2, s80
	s_mul_i32 s2, s0, 48
	s_add_i32 s2, s2, s15
	s_add_i32 s2, s2, -64
	v_add_u32_e32 v138, s2, v164
	v_and_b32_e32 v139, 3, v138
	v_lshlrev_b32_e32 v139, s13, v139
	v_bfe_u32 v140, v138, 2, 2
	v_add_u32_e32 v139, v139, v140
	v_lshl_add_u32 v139, v139, 7, v162
	v_ashrrev_i32_e32 v138, 4, v138
	v_med3_i32 v138, v138, 0, s14
	v_lshl_add_u32 v138, v138, 9, v139
	global_load_dwordx4 v[0:3], v138, s[20:21]
	s_mul_i32 s2, s0, 48
	s_add_i32 s2, s2, s15
	s_add_i32 s2, s2, -56
	v_add_u32_e32 v138, s2, v164
	v_and_b32_e32 v139, 3, v138
	v_lshlrev_b32_e32 v139, s13, v139
	v_bfe_u32 v140, v138, 2, 2
	v_add_u32_e32 v139, v139, v140
	v_lshl_add_u32 v139, v139, 7, v162
	v_ashrrev_i32_e32 v138, 4, v138
	v_med3_i32 v138, v138, 0, s14
	v_lshl_add_u32 v138, v138, 9, v139
	global_load_dwordx4 v[4:7], v138, s[20:21]
	s_mul_i32 s2, s0, 48
	s_add_i32 s2, s2, s15
	s_add_i32 s2, s2, -48
	v_add_u32_e32 v138, s2, v164
	v_and_b32_e32 v139, 3, v138
	v_lshlrev_b32_e32 v139, s13, v139
	v_bfe_u32 v140, v138, 2, 2
	v_add_u32_e32 v139, v139, v140
	v_lshl_add_u32 v139, v139, 7, v162
	v_ashrrev_i32_e32 v138, 4, v138
	v_med3_i32 v138, v138, 0, s14
	v_lshl_add_u32 v138, v138, 9, v139
	global_load_dwordx4 v[8:11], v138, s[20:21]
	s_mul_i32 s2, s0, 48
	s_add_i32 s2, s2, s15
	s_add_i32 s2, s2, -40
	v_add_u32_e32 v138, s2, v164
	v_and_b32_e32 v139, 3, v138
	v_lshlrev_b32_e32 v139, s13, v139
	v_bfe_u32 v140, v138, 2, 2
	v_add_u32_e32 v139, v139, v140
	v_lshl_add_u32 v139, v139, 7, v162
	v_ashrrev_i32_e32 v138, 4, v138
	v_med3_i32 v138, v138, 0, s14
	v_lshl_add_u32 v138, v138, 9, v139
	global_load_dwordx4 v[12:15], v138, s[20:21]
	s_lshl_b32 s2, s0, 5
	s_add_i32 s2, s2, s15
	s_add_i32 s2, s2, 0
	v_add_u32_e32 v138, s2, v164
	v_and_b32_e32 v139, 3, v138
	v_lshlrev_b32_e32 v139, s13, v139
	v_lshrrev_b32_e32 v140, 2, v138
	v_add_u32_e32 v139, v139, v140
	v_lshl_add_u32 v139, v139, 7, v162
	global_load_dwordx4 v[48:51], v139, s[18:19]
	s_lshl_b32 s2, s0, 5
	s_add_i32 s2, s2, s15
	s_add_i32 s2, s2, 8
	v_add_u32_e32 v138, s2, v164
	v_and_b32_e32 v139, 3, v138
	v_lshlrev_b32_e32 v139, s13, v139
	v_lshrrev_b32_e32 v140, 2, v138
	v_add_u32_e32 v139, v139, v140
	v_lshl_add_u32 v139, v139, 7, v162
	global_load_dwordx4 v[52:55], v139, s[18:19]
	s_lshl_b32 s2, s0, 5
	s_add_i32 s2, s2, s15
	s_add_i32 s2, s2, 16
	v_add_u32_e32 v138, s2, v164
	v_and_b32_e32 v139, 3, v138
	v_lshlrev_b32_e32 v139, s13, v139
	v_lshrrev_b32_e32 v140, 2, v138
	v_add_u32_e32 v139, v139, v140
	v_lshl_add_u32 v139, v139, 7, v162
	global_load_dwordx4 v[56:59], v139, s[18:19]
	s_lshl_b32 s2, s0, 5
	s_add_i32 s2, s2, s15
	s_add_i32 s2, s2, 24
	v_add_u32_e32 v138, s2, v164
	v_and_b32_e32 v139, 3, v138
	v_lshlrev_b32_e32 v139, s13, v139
	v_lshrrev_b32_e32 v140, 2, v138
	v_add_u32_e32 v139, v139, v140
	v_lshl_add_u32 v139, v139, 7, v162
	global_load_dwordx4 v[60:63], v139, s[18:19]
	ds_bpermute_b32 v142, v167, v132
	s_waitcnt lgkmcnt(0)
	v_add_f32_e32 v132, v132, v142
	ds_bpermute_b32 v142, v168, v132
	s_waitcnt lgkmcnt(0)
	v_add_f32_e32 v132, v132, v142
	ds_write_b128 v165, v[64:67]
	ds_write_b128 v165, v[68:71] offset:1152
	ds_write_b128 v165, v[72:75] offset:2304
	ds_write_b128 v165, v[76:79] offset:3456
	s_waitcnt lgkmcnt(0)
	ds_read_b64_tr_b16 v[236:237], v166
	ds_read_b64_tr_b16 v[238:239], v166 offset:2304
	ds_read_b64_tr_b16 v[240:241], v166 offset:32
	ds_read_b64_tr_b16 v[242:243], v166 offset:2336
	ds_read_b64_tr_b16 v[244:245], v166 offset:64
	ds_read_b64_tr_b16 v[246:247], v166 offset:2368
	ds_read_b64_tr_b16 v[248:249], v166 offset:96
	ds_read_b64_tr_b16 v[250:251], v166 offset:2400
	s_waitcnt lgkmcnt(0)
	ds_write_b128 v165, v[80:83]
	ds_write_b128 v165, v[84:87] offset:1152
	ds_write_b128 v165, v[88:91] offset:2304
	ds_write_b128 v165, v[92:95] offset:3456
	v_mfma_f32_16x16x32_bf16 v[204:207], v[236:239], v[112:115], 0
	v_mfma_f32_16x16x32_bf16 v[208:211], v[240:243], v[112:115], 0
	v_mfma_f32_16x16x32_bf16 v[212:215], v[244:247], v[112:115], 0
	v_mfma_f32_16x16x32_bf16 v[216:219], v[248:251], v[112:115], 0
	s_waitcnt lgkmcnt(0)
	ds_read_b64_tr_b16 v[236:237], v166
	ds_read_b64_tr_b16 v[238:239], v166 offset:2304
	ds_read_b64_tr_b16 v[240:241], v166 offset:32
	ds_read_b64_tr_b16 v[242:243], v166 offset:2336
	ds_read_b64_tr_b16 v[244:245], v166 offset:64
	ds_read_b64_tr_b16 v[246:247], v166 offset:2368
	ds_read_b64_tr_b16 v[248:249], v166 offset:96
	ds_read_b64_tr_b16 v[250:251], v166 offset:2400
	s_waitcnt lgkmcnt(0)
	ds_write_b128 v165, v[96:99]
	ds_write_b128 v165, v[100:103] offset:1152
	ds_write_b128 v165, v[104:107] offset:2304
	ds_write_b128 v165, v[108:111] offset:3456
	v_mfma_f32_16x16x32_bf16 v[204:207], v[236:239], v[116:119], v[204:207]
	v_mfma_f32_16x16x32_bf16 v[208:211], v[240:243], v[116:119], v[208:211]
	v_mfma_f32_16x16x32_bf16 v[212:215], v[244:247], v[116:119], v[212:215]
	v_mfma_f32_16x16x32_bf16 v[216:219], v[248:251], v[116:119], v[216:219]
	s_waitcnt lgkmcnt(0)
	ds_read_b64_tr_b16 v[236:237], v166
	ds_read_b64_tr_b16 v[238:239], v166 offset:2304
	ds_read_b64_tr_b16 v[240:241], v166 offset:32
	ds_read_b64_tr_b16 v[242:243], v166 offset:2336
	ds_read_b64_tr_b16 v[244:245], v166 offset:64
	ds_read_b64_tr_b16 v[246:247], v166 offset:2368
	ds_read_b64_tr_b16 v[248:249], v166 offset:96
	ds_read_b64_tr_b16 v[250:251], v166 offset:2400
	s_waitcnt lgkmcnt(0)
	s_waitcnt vmcnt(10)
	ds_write_b128 v165, v[16:19]
	ds_write_b128 v165, v[20:23] offset:1152
	ds_write_b128 v165, v[24:27] offset:2304
	ds_write_b128 v165, v[28:31] offset:3456
	v_mfma_f32_16x16x32_bf16 v[204:207], v[236:239], v[120:123], v[204:207]
	v_mfma_f32_16x16x32_bf16 v[208:211], v[240:243], v[120:123], v[208:211]
	v_mfma_f32_16x16x32_bf16 v[212:215], v[244:247], v[120:123], v[212:215]
	v_mfma_f32_16x16x32_bf16 v[216:219], v[248:251], v[120:123], v[216:219]
	s_waitcnt lgkmcnt(0)
	ds_read_b64_tr_b16 v[236:237], v166
	ds_read_b64_tr_b16 v[238:239], v166 offset:2304
	ds_read_b64_tr_b16 v[240:241], v166 offset:32
	ds_read_b64_tr_b16 v[242:243], v166 offset:2336
	ds_read_b64_tr_b16 v[244:245], v166 offset:64
	ds_read_b64_tr_b16 v[246:247], v166 offset:2368
	ds_read_b64_tr_b16 v[248:249], v166 offset:96
	ds_read_b64_tr_b16 v[250:251], v166 offset:2400
	s_waitcnt lgkmcnt(0)
	s_mul_i32 s2, s0, 48
	s_add_i32 s2, s2, s15
	s_add_i32 s2, s2, -32
	v_add_u32_e32 v138, s2, v164
	v_and_b32_e32 v139, 3, v138
	v_lshlrev_b32_e32 v139, s13, v139
	v_bfe_u32 v140, v138, 2, 2
	v_add_u32_e32 v139, v139, v140
	v_lshl_add_u32 v139, v139, 7, v162
	v_ashrrev_i32_e32 v138, 4, v138
	v_med3_i32 v138, v138, 0, s14
	v_lshl_add_u32 v138, v138, 9, v139
	global_load_dwordx4 v[16:19], v138, s[20:21]
	s_mul_i32 s2, s0, 48
	s_add_i32 s2, s2, s15
	s_add_i32 s2, s2, -24
	v_add_u32_e32 v138, s2, v164
	v_and_b32_e32 v139, 3, v138
	v_lshlrev_b32_e32 v139, s13, v139
	v_bfe_u32 v140, v138, 2, 2
	v_add_u32_e32 v139, v139, v140
	v_lshl_add_u32 v139, v139, 7, v162
	v_ashrrev_i32_e32 v138, 4, v138
	v_med3_i32 v138, v138, 0, s14
	v_lshl_add_u32 v138, v138, 9, v139
	global_load_dwordx4 v[20:23], v138, s[20:21]
	s_mul_i32 s2, s0, 48
	s_add_i32 s2, s2, s15
	s_add_i32 s2, s2, -64
	v_add_u32_e32 v138, s2, v164
	v_and_b32_e32 v139, 3, v138
	v_lshlrev_b32_e32 v139, s13, v139
	v_bfe_u32 v140, v138, 2, 2
	v_add_u32_e32 v139, v139, v140
	v_lshl_add_u32 v139, v139, 7, v162
	v_ashrrev_i32_e32 v138, 4, v138
	v_med3_i32 v138, v138, 0, s14
	v_lshl_add_u32 v138, v138, 9, v139
	global_load_dwordx4 v[24:27], v138, s[22:23]
	s_mul_i32 s2, s0, 48
	s_add_i32 s2, s2, s15
	s_add_i32 s2, s2, -56
	v_add_u32_e32 v138, s2, v164
	v_and_b32_e32 v139, 3, v138
	v_lshlrev_b32_e32 v139, s13, v139
	v_bfe_u32 v140, v138, 2, 2
	v_add_u32_e32 v139, v139, v140
	v_lshl_add_u32 v139, v139, 7, v162
	v_ashrrev_i32_e32 v138, 4, v138
	v_med3_i32 v138, v138, 0, s14
	v_lshl_add_u32 v138, v138, 9, v139
	global_load_dwordx4 v[28:31], v138, s[22:23]
	s_waitcnt vmcnt(12)
	ds_write_b128 v165, v[32:35]
	ds_write_b128 v165, v[36:39] offset:1152
	v_mfma_f32_16x16x32_bf16 v[204:207], v[236:239], v[124:127], v[204:207]
	v_mfma_f32_16x16x32_bf16 v[208:211], v[240:243], v[124:127], v[208:211]
	v_mfma_f32_16x16x32_bf16 v[212:215], v[244:247], v[124:127], v[212:215]
	v_mfma_f32_16x16x32_bf16 v[216:219], v[248:251], v[124:127], v[216:219]
	s_waitcnt lgkmcnt(0)
	ds_read_b64_tr_b16 v[236:237], v166
	ds_read_b64_tr_b16 v[238:239], v166 offset:2304
	ds_read_b64_tr_b16 v[240:241], v166 offset:32
	ds_read_b64_tr_b16 v[242:243], v166 offset:2336
	ds_read_b64_tr_b16 v[244:245], v166 offset:64
	ds_read_b64_tr_b16 v[246:247], v166 offset:2368
	ds_read_b64_tr_b16 v[248:249], v166 offset:96
	ds_read_b64_tr_b16 v[250:251], v166 offset:2400
	s_waitcnt lgkmcnt(0)
	s_mul_i32 s2, s0, 48
	s_add_i32 s2, s2, s15
	s_add_i32 s2, s2, -48
	v_add_u32_e32 v138, s2, v164
	v_and_b32_e32 v139, 3, v138
	v_lshlrev_b32_e32 v139, s13, v139
	v_bfe_u32 v140, v138, 2, 2
	v_add_u32_e32 v139, v139, v140
	v_lshl_add_u32 v139, v139, 7, v162
	v_ashrrev_i32_e32 v138, 4, v138
	v_med3_i32 v138, v138, 0, s14
	v_lshl_add_u32 v138, v138, 9, v139
	global_load_dwordx4 v[32:35], v138, s[22:23]
	s_mul_i32 s2, s0, 48
	s_add_i32 s2, s2, s15
	s_add_i32 s2, s2, -40
	v_add_u32_e32 v138, s2, v164
	v_and_b32_e32 v139, 3, v138
	v_lshlrev_b32_e32 v139, s13, v139
	v_bfe_u32 v140, v138, 2, 2
	v_add_u32_e32 v139, v139, v140
	v_lshl_add_u32 v139, v139, 7, v162
	v_ashrrev_i32_e32 v138, 4, v138
	v_med3_i32 v138, v138, 0, s14
	v_lshl_add_u32 v138, v138, 9, v139
	global_load_dwordx4 v[36:39], v138, s[22:23]
	s_mul_i32 s2, s0, 48
	s_add_i32 s2, s2, s15
	s_add_i32 s2, s2, -32
	v_add_u32_e32 v138, s2, v164
	v_and_b32_e32 v139, 3, v138
	v_lshlrev_b32_e32 v139, s13, v139
	v_bfe_u32 v140, v138, 2, 2
	v_add_u32_e32 v139, v139, v140
	v_lshl_add_u32 v139, v139, 7, v162
	v_ashrrev_i32_e32 v138, 4, v138
	v_med3_i32 v138, v138, 0, s14
	v_lshl_add_u32 v138, v138, 9, v139
	global_load_dwordx4 v[40:43], v138, s[22:23]
	s_mul_i32 s2, s0, 48
	s_add_i32 s2, s2, s15
	s_add_i32 s2, s2, -24
	v_add_u32_e32 v138, s2, v164
	v_and_b32_e32 v139, 3, v138
	v_lshlrev_b32_e32 v139, s13, v139
	v_bfe_u32 v140, v138, 2, 2
	v_add_u32_e32 v139, v139, v140
	v_lshl_add_u32 v139, v139, 7, v162
	v_ashrrev_i32_e32 v138, 4, v138
	v_med3_i32 v138, v138, 0, s14
	v_lshl_add_u32 v138, v138, 9, v139
	global_load_dwordx4 v[44:47], v138, s[22:23]
	v_mfma_f32_16x16x32_bf16 v[204:207], v[236:239], v[128:131], v[204:207]
	v_mfma_f32_16x16x32_bf16 v[208:211], v[240:243], v[128:131], v[208:211]
	v_mfma_f32_16x16x32_bf16 v[212:215], v[244:247], v[128:131], v[212:215]
	v_mfma_f32_16x16x32_bf16 v[216:219], v[248:251], v[128:131], v[216:219]
	ds_read_b128 v[236:239], v173 offset:0
	ds_read_b128 v[240:243], v173 offset:64
	ds_read_b128 v[244:247], v173 offset:128
	ds_read_b128 v[248:251], v173 offset:192
	ds_read_b32 v142, v174 offset:0
	s_waitcnt lgkmcnt(0)
	v_add_f32_e32 v204, v236, v204
	v_add_f32_e32 v205, v237, v205
	v_add_f32_e32 v206, v238, v206
	v_add_f32_e32 v207, v239, v207
	v_add_f32_e32 v208, v240, v208
	v_add_f32_e32 v209, v241, v209
	v_add_f32_e32 v210, v242, v210
	v_add_f32_e32 v211, v243, v211
	v_add_f32_e32 v212, v244, v212
	v_add_f32_e32 v213, v245, v213
	v_add_f32_e32 v214, v246, v214
	v_add_f32_e32 v215, v247, v215
	v_add_f32_e32 v216, v248, v216
	v_add_f32_e32 v217, v249, v217
	v_add_f32_e32 v218, v250, v218
	v_add_f32_e32 v219, v251, v219
	v_add_f32_e32 v132, v142, v132
	ds_write_b128 v173, v[204:207] offset:0
	ds_write_b128 v173, v[208:211] offset:64
	ds_write_b128 v173, v[212:215] offset:128
	ds_write_b128 v173, v[216:219] offset:192
	ds_write_b32 v174, v132 offset:0
	s_waitcnt lgkmcnt(0)
	s_barrier
	ds_read_b128 v[204:207], v170
	ds_read_b128 v[208:211], v170 offset:16
	ds_read_b128 v[212:215], v170 offset:32
	ds_read_b128 v[216:219], v170 offset:48
	ds_read_b128 v[220:223], v170 offset:64
	ds_read_b128 v[224:227], v170 offset:80
	ds_read_b128 v[228:231], v170 offset:96
	ds_read_b128 v[232:235], v170 offset:112
	ds_read_b32 v142, v171
	s_lshl_b32 s2, s35, 11
	s_lshl_b32 s3, s36, 7
	s_add_u32 s2, s2, s3
	s_add_u32 s90, s6, s2
	s_addc_u32 s91, s7, 0
	s_waitcnt lgkmcnt(0)
	v_div_scale_f32 v143, s[30:31], v142, v142, 1.0
	v_rcp_f32_e32 v147, v143
	v_div_scale_f32 v134, vcc, 1.0, v142, 1.0
	v_fma_f32 v135, -v143, v147, 1.0
	v_fmac_f32_e32 v147, v135, v147
	v_mul_f32_e32 v135, v134, v147
	v_fma_f32 v136, -v143, v135, v134
	v_fmac_f32_e32 v135, v136, v147
	v_fma_f32 v143, -v143, v135, v134
	v_div_fmas_f32 v143, v143, v147, v135
	v_div_fixup_f32 v142, v143, v142, 1.0
	v_mul_f32_e32 v204, v142, v204
	v_mul_f32_e32 v205, v142, v205
	v_mul_f32_e32 v206, v142, v206
	v_mul_f32_e32 v207, v142, v207
	v_mul_f32_e32 v208, v142, v208
	v_mul_f32_e32 v209, v142, v209
	v_mul_f32_e32 v210, v142, v210
	v_mul_f32_e32 v211, v142, v211
	v_mul_f32_e32 v212, v142, v212
	v_mul_f32_e32 v213, v142, v213
	v_mul_f32_e32 v214, v142, v214
	v_mul_f32_e32 v215, v142, v215
	v_mul_f32_e32 v216, v142, v216
	v_mul_f32_e32 v217, v142, v217
	v_mul_f32_e32 v218, v142, v218
	v_mul_f32_e32 v219, v142, v219
	v_mul_f32_e32 v220, v142, v220
	v_mul_f32_e32 v221, v142, v221
	v_mul_f32_e32 v222, v142, v222
	v_mul_f32_e32 v223, v142, v223
	v_mul_f32_e32 v224, v142, v224
	v_mul_f32_e32 v225, v142, v225
	v_mul_f32_e32 v226, v142, v226
	v_mul_f32_e32 v227, v142, v227
	v_mul_f32_e32 v228, v142, v228
	v_mul_f32_e32 v229, v142, v229
	v_mul_f32_e32 v230, v142, v230
	v_mul_f32_e32 v231, v142, v231
	v_mul_f32_e32 v232, v142, v232
	v_mul_f32_e32 v233, v142, v233
	v_mul_f32_e32 v234, v142, v234
	v_mul_f32_e32 v235, v142, v235
	v_cvt_pk_bf16_f32 v112, v204, v205
	v_cvt_pk_bf16_f32 v113, v206, v207
	v_cvt_pk_bf16_f32 v114, v208, v209
	v_cvt_pk_bf16_f32 v115, v210, v211
	v_cvt_pk_bf16_f32 v116, v212, v213
	v_cvt_pk_bf16_f32 v117, v214, v215
	v_cvt_pk_bf16_f32 v118, v216, v217
	v_cvt_pk_bf16_f32 v119, v218, v219
	v_cvt_pk_bf16_f32 v120, v220, v221
	v_cvt_pk_bf16_f32 v121, v222, v223
	v_cvt_pk_bf16_f32 v122, v224, v225
	v_cvt_pk_bf16_f32 v123, v226, v227
	v_cvt_pk_bf16_f32 v124, v228, v229
	v_cvt_pk_bf16_f32 v125, v230, v231
	v_cvt_pk_bf16_f32 v126, v232, v233
	v_cvt_pk_bf16_f32 v127, v234, v235
	global_store_dwordx4 v172, v[112:115], s[90:91] nt
	global_store_dwordx4 v172, v[116:119], s[90:91] offset:16 nt
	global_store_dwordx4 v172, v[120:123], s[90:91] offset:32 nt
	global_store_dwordx4 v172, v[124:127], s[90:91] offset:48 nt
	s_barrier
	s_cmp_eq_u32 s37, 0
	s_cbranch_scc1 .Latt_unit
	s_waitcnt vmcnt(0)
	s_branch .LBB0_365
